# epilogue stores widened to dwordx4 via permlane32_swap pairs (w_in, FFN-up, w_out and FFN1-down residual epilogues) on top of 16x16x32 MFMA GEMM loops
# speedup vs baseline: 1.0245x; 1.0069x over previous
; __device__ __forceinline__ int ltid() { int t = threadIdx.x; asm volatile("" : "+v"(t)); return t; }
; __device__ __forceinline__ float sigm(float x) { return __builtin_amdgcn_rcpf(1.f + __builtin_amdgcn_exp2f(-LOG2E * x)); }
; __device__ __forceinline__ void epi_swiglu(const f32x16 (&acc)[2][2], int nbase, int tbase, int M, const float* ss, u16* ACT) {
;   const int lane = ltid() & 63, l32 = lane & 31, h = lane >> 5;
;   const int cb = (nbase >> 6) * 32;
; #pragma unroll
;   for (int tb = 0; tb < 2; ++tb) {
;     const int tok = tbase + tb * 32 + l32;
;     if (tok < M) {
;       const float rs = rsqrtf(ss[tok] * (1.f / 1024.f) + EPSN);
;       u16* dst = ACT + (size_t)tok * FFD + cb + 4 * h;
; #pragma unroll
;       for (int i = 0; i < 4; ++i) {
;         float o[4];
; #pragma unroll
;         for (int j = 0; j < 4; ++j) {
;           const float g = acc[0][tb][4 * i + j] * rs, u = acc[1][tb][4 * i + j] * rs;
;           o[j] = g * sigm(g) * u;
;         }
;         *(u32x2*)(dst + 8 * i) = (u32x2){pk_bf16(o[0], o[1]), pk_bf16(o[2], o[3])};
;       }
;     }
;   }
.LBB0_93:
	s_or_b64 exec, exec, s[6:7]
	v_mov_b32_e32 v146, v204
	s_load_dwordx2 s[0:1], s[64:65], 0x1c8
	v_lshl_or_b32 v144, v170, 7, v168
	v_lshl_add_u32 v155, v160, 8, v169
	v_ashrrev_i32_e32 v144, 1, v144
	v_and_or_b32 v148, v146, 31, v155
	v_ashrrev_i32_e32 v145, 31, v144
	v_lshrrev_b32_e32 v146, 2, v146
	s_waitcnt lgkmcnt(0)
	v_lshl_add_u64 v[144:145], v[144:145], 1, s[0:1]
	v_and_b32_e32 v160, 8, v146
	v_lshl_add_u64 v[146:147], v[144:145], 0, v[160:161]
	v_cmp_gt_i32_e64 s[40:41], s62, v148
	v_ashrrev_i32_e32 v149, 31, v148
	s_and_saveexec_b64 s[34:35], s[40:41]
	s_cbranch_execz .LBB0_95
	v_lshl_add_u64 v[150:151], v[148:149], 2, s[44:45]
	global_load_dword v150, v[150:151], off
	s_waitcnt vmcnt(0)
	v_fmamk_f32 v150, v150, 0x3a800000, v205
	v_cmp_gt_f32_e64 s[40:41], s21, v150
	v_mul_f32_e32 v151, 0x4b800000, v150
	s_nop 0
	v_cndmask_b32_e64 v150, v150, v151, s[40:41]
	v_rsq_f32_e32 v150, v150
	s_nop 0
	v_mul_f32_e32 v151, 0x45800000, v150
	v_cndmask_b32_e64 v152, v150, v151, s[40:41]
	v_pk_mul_f32 v[112:113], v[112:113], v[152:153] op_sel_hi:[1,0]
	v_pk_mul_f32 v[96:97], v[96:97], v[152:153] op_sel_hi:[1,0]
	v_mul_f32_e32 v160, 0xbfb8aa3b, v112
	v_exp_f32_e32 v160, v160
	v_pk_mul_f32 v[98:99], v[98:99], v[152:153] op_sel_hi:[1,0]
	v_mad_i64_i32 v[150:151], s[0:1], v148, s56, v[146:147]
	v_add_f32_e32 v160, 1.0, v160
	v_rcp_f32_e32 v170, v160
	v_mul_f32_e32 v160, 0xbfb8aa3b, v113
	v_exp_f32_e32 v160, v160
	v_pk_mul_f32 v[100:101], v[100:101], v[152:153] op_sel_hi:[1,0]
	v_pk_mul_f32 v[102:103], v[102:103], v[152:153] op_sel_hi:[1,0]
	v_add_f32_e32 v160, 1.0, v160
	v_rcp_f32_e32 v171, v160
	s_nop 0
	v_pk_mul_f32 v[112:113], v[112:113], v[170:171]
	s_nop 0
	v_pk_mul_f32 v[96:97], v[96:97], v[112:113]
	v_pk_mul_f32 v[112:113], v[114:115], v[152:153] op_sel_hi:[1,0]
	v_cvt_pk_bf16_f32 v96, v96, v97
	v_mul_f32_e32 v114, 0xbfb8aa3b, v112
	v_mul_f32_e32 v115, 0xbfb8aa3b, v113
	v_exp_f32_e32 v114, v114
	v_exp_f32_e32 v115, v115
	v_add_f32_e32 v114, 1.0, v114
	v_add_f32_e32 v115, 1.0, v115
	v_rcp_f32_e32 v114, v114
	v_rcp_f32_e32 v115, v115
	s_nop 0
	v_pk_mul_f32 v[112:113], v[112:113], v[114:115]
	s_nop 0
	v_pk_mul_f32 v[98:99], v[98:99], v[112:113]
	s_nop 0
	v_cvt_pk_bf16_f32 v97, v98, v99
	v_mov_b32_e32 v222, v96
	v_mov_b32_e32 v223, v97
	v_pk_mul_f32 v[96:97], v[116:117], v[152:153] op_sel_hi:[1,0]
	s_nop 0
	v_mul_f32_e32 v98, 0xbfb8aa3b, v96
	v_mul_f32_e32 v99, 0xbfb8aa3b, v97
	v_exp_f32_e32 v98, v98
	v_exp_f32_e32 v99, v99
	v_add_f32_e32 v98, 1.0, v98
	v_add_f32_e32 v99, 1.0, v99
	v_rcp_f32_e32 v98, v98
	v_rcp_f32_e32 v99, v99
	s_nop 0
	v_pk_mul_f32 v[96:97], v[96:97], v[98:99]
	v_pk_mul_f32 v[98:99], v[118:119], v[152:153] op_sel_hi:[1,0]
	v_pk_mul_f32 v[96:97], v[100:101], v[96:97]
	v_mul_f32_e32 v100, 0xbfb8aa3b, v98
	v_mul_f32_e32 v101, 0xbfb8aa3b, v99
	v_exp_f32_e32 v100, v100
	v_exp_f32_e32 v101, v101
	v_cvt_pk_bf16_f32 v96, v96, v97
	v_add_f32_e32 v100, 1.0, v100
	v_add_f32_e32 v101, 1.0, v101
	v_rcp_f32_e32 v100, v100
	v_rcp_f32_e32 v101, v101
	s_nop 0
	v_pk_mul_f32 v[98:99], v[98:99], v[100:101]
	s_nop 0
	v_pk_mul_f32 v[98:99], v[102:103], v[98:99]
	v_pk_mul_f32 v[100:101], v[104:105], v[152:153] op_sel_hi:[1,0]
	v_cvt_pk_bf16_f32 v97, v98, v99
	v_mov_b32_e32 v224, v96
	v_mov_b32_e32 v225, v97
	v_lshrrev_b32_e32 v238, 2, v204
	v_and_b32_e32 v238, 8, v238
	v_mov_b32_e32 v239, 0
	v_lshl_add_u64 v[240:241], v[150:151], 0, v[238:239]
	v_permlane32_swap_b32_e32 v222, v224
	v_permlane32_swap_b32_e32 v223, v225
	global_store_dwordx4 v[240:241], v[222:225], off
	v_pk_mul_f32 v[96:97], v[120:121], v[152:153] op_sel_hi:[1,0]
	v_pk_mul_f32 v[102:103], v[106:107], v[152:153] op_sel_hi:[1,0]
	v_mul_f32_e32 v98, 0xbfb8aa3b, v96
	v_mul_f32_e32 v99, 0xbfb8aa3b, v97
	v_exp_f32_e32 v98, v98
	v_exp_f32_e32 v99, v99
	v_add_f32_e32 v98, 1.0, v98
	v_add_f32_e32 v99, 1.0, v99
	v_rcp_f32_e32 v98, v98
	v_rcp_f32_e32 v99, v99
	s_nop 0
	v_pk_mul_f32 v[96:97], v[96:97], v[98:99]
	v_pk_mul_f32 v[98:99], v[122:123], v[152:153] op_sel_hi:[1,0]
	v_pk_mul_f32 v[96:97], v[100:101], v[96:97]
	v_mul_f32_e32 v100, 0xbfb8aa3b, v98
	v_mul_f32_e32 v101, 0xbfb8aa3b, v99
	v_exp_f32_e32 v100, v100
	v_exp_f32_e32 v101, v101
	v_cvt_pk_bf16_f32 v96, v96, v97
	v_add_f32_e32 v100, 1.0, v100
	v_add_f32_e32 v101, 1.0, v101
	v_rcp_f32_e32 v100, v100
	v_rcp_f32_e32 v101, v101
	s_nop 0
	v_pk_mul_f32 v[98:99], v[98:99], v[100:101]
	s_nop 0
	v_pk_mul_f32 v[98:99], v[102:103], v[98:99]
	v_pk_mul_f32 v[100:101], v[108:109], v[152:153] op_sel_hi:[1,0]
	v_cvt_pk_bf16_f32 v97, v98, v99
	v_mov_b32_e32 v226, v96
	v_mov_b32_e32 v227, v97
	v_pk_mul_f32 v[96:97], v[124:125], v[152:153] op_sel_hi:[1,0]
	v_pk_mul_f32 v[102:103], v[110:111], v[152:153] op_sel_hi:[1,0]
	v_mul_f32_e32 v98, 0xbfb8aa3b, v96
	v_mul_f32_e32 v99, 0xbfb8aa3b, v97
	v_exp_f32_e32 v98, v98
	v_exp_f32_e32 v99, v99
	v_add_f32_e32 v98, 1.0, v98
	v_add_f32_e32 v99, 1.0, v99
	v_rcp_f32_e32 v98, v98
	v_rcp_f32_e32 v99, v99
	s_nop 0
	v_pk_mul_f32 v[96:97], v[96:97], v[98:99]
	v_pk_mul_f32 v[98:99], v[126:127], v[152:153] op_sel_hi:[1,0]
	v_pk_mul_f32 v[96:97], v[100:101], v[96:97]
	v_mul_f32_e32 v100, 0xbfb8aa3b, v98
	v_mul_f32_e32 v101, 0xbfb8aa3b, v99
	v_exp_f32_e32 v100, v100
	v_exp_f32_e32 v101, v101
	v_cvt_pk_bf16_f32 v96, v96, v97
	v_add_f32_e32 v100, 1.0, v100
	v_add_f32_e32 v101, 1.0, v101
	v_rcp_f32_e32 v100, v100
	v_rcp_f32_e32 v101, v101
	s_nop 0
	v_pk_mul_f32 v[98:99], v[98:99], v[100:101]
	s_nop 0
	v_pk_mul_f32 v[98:99], v[102:103], v[98:99]
	s_nop 0
	v_cvt_pk_bf16_f32 v97, v98, v99
	v_mov_b32_e32 v228, v96
	v_mov_b32_e32 v229, v97
	s_nop 1
	v_permlane32_swap_b32_e32 v226, v228
	v_permlane32_swap_b32_e32 v227, v229
	global_store_dwordx4 v[240:241], v[226:229], off offset:32
; __device__ __forceinline__ int ltid() { int t = threadIdx.x; asm volatile("" : "+v"(t)); return t; }
; __device__ __forceinline__ float sigm(float x) { return __builtin_amdgcn_rcpf(1.f + __builtin_amdgcn_exp2f(-LOG2E * x)); }
; __device__ __forceinline__ void epi_swiglu(const f32x16 (&acc)[2][2], int nbase, int tbase, int M, const float* ss, u16* ACT) {
;   const int lane = ltid() & 63, l32 = lane & 31, h = lane >> 5;
;   const int cb = (nbase >> 6) * 32;
; #pragma unroll
;   for (int tb = 0; tb < 2; ++tb) {
;     const int tok = tbase + tb * 32 + l32;
;     if (tok < M) {
;       const float rs = rsqrtf(ss[tok] * (1.f / 1024.f) + EPSN);
;       u16* dst = ACT + (size_t)tok * FFD + cb + 4 * h;
; #pragma unroll
;       for (int i = 0; i < 4; ++i) {
;         float o[4];
; #pragma unroll
;         for (int j = 0; j < 4; ++j) {
;           const float g = acc[0][tb][4 * i + j] * rs, u = acc[1][tb][4 * i + j] * rs;
;           o[j] = g * sigm(g) * u;
;         }
;         *(u32x2*)(dst + 8 * i) = (u32x2){pk_bf16(o[0], o[1]), pk_bf16(o[2], o[3])};
;       }
;     }
;   }
.LBB0_95:
	s_or_b64 exec, exec, s[34:35]
	v_or_b32_e32 v96, 32, v148
	v_cmp_gt_i32_e64 s[40:41], s62, v96
	s_and_saveexec_b64 s[34:35], s[40:41]
	s_cbranch_execz .LBB0_97
	v_lshl_add_u64 v[98:99], v[148:149], 2, s[44:45]
	global_load_dword v97, v[98:99], off offset:128
	s_waitcnt vmcnt(0)
	v_fmamk_f32 v97, v97, 0x3a800000, v205
	v_cmp_gt_f32_e64 s[40:41], s21, v97
	v_mul_f32_e32 v98, 0x4b800000, v97
	s_nop 0
	v_cndmask_b32_e64 v97, v97, v98, s[40:41]
	v_rsq_f32_e32 v97, v97
	s_nop 0
	v_mul_f32_e32 v98, 0x45800000, v97
	v_cndmask_b32_e64 v98, v97, v98, s[40:41]
	v_pk_mul_f32 v[80:81], v[80:81], v[98:99] op_sel_hi:[1,0]
	v_mad_i64_i32 v[96:97], s[0:1], v96, s56, v[146:147]
	v_mul_f32_e32 v99, 0xbfb8aa3b, v80
	v_exp_f32_e32 v99, v99
	s_nop 0
	v_add_f32_e32 v99, 1.0, v99
	v_rcp_f32_e32 v100, v99
	v_pk_mul_f32 v[64:65], v[64:65], v[98:99] op_sel_hi:[1,0]
	v_mul_f32_e32 v99, 0xbfb8aa3b, v81
	v_exp_f32_e32 v99, v99
	s_nop 0
	v_add_f32_e32 v99, 1.0, v99
	v_rcp_f32_e32 v101, v99
	v_pk_mul_f32 v[66:67], v[66:67], v[98:99] op_sel_hi:[1,0]
	v_pk_mul_f32 v[68:69], v[68:69], v[98:99] op_sel_hi:[1,0]
	v_pk_mul_f32 v[70:71], v[70:71], v[98:99] op_sel_hi:[1,0]
	v_pk_mul_f32 v[80:81], v[80:81], v[100:101]
	s_nop 0
	v_pk_mul_f32 v[64:65], v[64:65], v[80:81]
	v_pk_mul_f32 v[80:81], v[82:83], v[98:99] op_sel_hi:[1,0]
	v_cvt_pk_bf16_f32 v64, v64, v65
	v_mul_f32_e32 v82, 0xbfb8aa3b, v80
	v_mul_f32_e32 v83, 0xbfb8aa3b, v81
	v_exp_f32_e32 v82, v82
	v_exp_f32_e32 v83, v83
	v_add_f32_e32 v82, 1.0, v82
	v_add_f32_e32 v83, 1.0, v83
	v_rcp_f32_e32 v82, v82
	v_rcp_f32_e32 v83, v83
	s_nop 0
	v_pk_mul_f32 v[80:81], v[80:81], v[82:83]
	s_nop 0
	v_pk_mul_f32 v[66:67], v[66:67], v[80:81]
	s_nop 0
	v_cvt_pk_bf16_f32 v65, v66, v67
	v_mov_b32_e32 v230, v64
	v_mov_b32_e32 v231, v65
	v_pk_mul_f32 v[64:65], v[84:85], v[98:99] op_sel_hi:[1,0]
	s_nop 0
	v_mul_f32_e32 v66, 0xbfb8aa3b, v64
	v_mul_f32_e32 v67, 0xbfb8aa3b, v65
	v_exp_f32_e32 v66, v66
	v_exp_f32_e32 v67, v67
	v_add_f32_e32 v66, 1.0, v66
	v_add_f32_e32 v67, 1.0, v67
	v_rcp_f32_e32 v66, v66
	v_rcp_f32_e32 v67, v67
	s_nop 0
	v_pk_mul_f32 v[64:65], v[64:65], v[66:67]
	v_pk_mul_f32 v[66:67], v[86:87], v[98:99] op_sel_hi:[1,0]
	v_pk_mul_f32 v[64:65], v[68:69], v[64:65]
	v_mul_f32_e32 v68, 0xbfb8aa3b, v66
	v_mul_f32_e32 v69, 0xbfb8aa3b, v67
	v_exp_f32_e32 v68, v68
	v_exp_f32_e32 v69, v69
	v_cvt_pk_bf16_f32 v64, v64, v65
	v_add_f32_e32 v68, 1.0, v68
	v_add_f32_e32 v69, 1.0, v69
	v_rcp_f32_e32 v68, v68
	v_rcp_f32_e32 v69, v69
	s_nop 0
	v_pk_mul_f32 v[66:67], v[66:67], v[68:69]
	s_nop 0
	v_pk_mul_f32 v[66:67], v[70:71], v[66:67]
	v_pk_mul_f32 v[68:69], v[72:73], v[98:99] op_sel_hi:[1,0]
	v_cvt_pk_bf16_f32 v65, v66, v67
	v_mov_b32_e32 v232, v64
	v_mov_b32_e32 v233, v65
	v_lshrrev_b32_e32 v238, 2, v204
	v_and_b32_e32 v238, 8, v238
	v_mov_b32_e32 v239, 0
	v_lshl_add_u64 v[240:241], v[96:97], 0, v[238:239]
	v_permlane32_swap_b32_e32 v230, v232
	v_permlane32_swap_b32_e32 v231, v233
	global_store_dwordx4 v[240:241], v[230:233], off
	v_pk_mul_f32 v[64:65], v[88:89], v[98:99] op_sel_hi:[1,0]
	v_pk_mul_f32 v[70:71], v[74:75], v[98:99] op_sel_hi:[1,0]
	v_mul_f32_e32 v66, 0xbfb8aa3b, v64
	v_mul_f32_e32 v67, 0xbfb8aa3b, v65
	v_exp_f32_e32 v66, v66
	v_exp_f32_e32 v67, v67
	v_add_f32_e32 v66, 1.0, v66
	v_add_f32_e32 v67, 1.0, v67
	v_rcp_f32_e32 v66, v66
	v_rcp_f32_e32 v67, v67
	s_nop 0
	v_pk_mul_f32 v[64:65], v[64:65], v[66:67]
	v_pk_mul_f32 v[66:67], v[90:91], v[98:99] op_sel_hi:[1,0]
	v_pk_mul_f32 v[64:65], v[68:69], v[64:65]
	v_mul_f32_e32 v68, 0xbfb8aa3b, v66
	v_mul_f32_e32 v69, 0xbfb8aa3b, v67
	v_exp_f32_e32 v68, v68
	v_exp_f32_e32 v69, v69
	v_cvt_pk_bf16_f32 v64, v64, v65
	v_add_f32_e32 v68, 1.0, v68
	v_add_f32_e32 v69, 1.0, v69
	v_rcp_f32_e32 v68, v68
	v_rcp_f32_e32 v69, v69
	s_nop 0
	v_pk_mul_f32 v[66:67], v[66:67], v[68:69]
	s_nop 0
	v_pk_mul_f32 v[66:67], v[70:71], v[66:67]
	v_pk_mul_f32 v[68:69], v[76:77], v[98:99] op_sel_hi:[1,0]
	v_cvt_pk_bf16_f32 v65, v66, v67
	v_mov_b32_e32 v234, v64
	v_mov_b32_e32 v235, v65
	v_pk_mul_f32 v[64:65], v[92:93], v[98:99] op_sel_hi:[1,0]
	v_pk_mul_f32 v[70:71], v[78:79], v[98:99] op_sel_hi:[1,0]
	v_mul_f32_e32 v66, 0xbfb8aa3b, v64
	v_mul_f32_e32 v67, 0xbfb8aa3b, v65
	v_exp_f32_e32 v66, v66
	v_exp_f32_e32 v67, v67
	v_add_f32_e32 v66, 1.0, v66
	v_add_f32_e32 v67, 1.0, v67
	v_rcp_f32_e32 v66, v66
	v_rcp_f32_e32 v67, v67
	s_nop 0
	v_pk_mul_f32 v[64:65], v[64:65], v[66:67]
	v_pk_mul_f32 v[66:67], v[94:95], v[98:99] op_sel_hi:[1,0]
	v_pk_mul_f32 v[64:65], v[68:69], v[64:65]
	v_mul_f32_e32 v68, 0xbfb8aa3b, v66
	v_mul_f32_e32 v69, 0xbfb8aa3b, v67
	v_exp_f32_e32 v68, v68
	v_exp_f32_e32 v69, v69
	v_cvt_pk_bf16_f32 v64, v64, v65
	v_add_f32_e32 v68, 1.0, v68
	v_add_f32_e32 v69, 1.0, v69
	v_rcp_f32_e32 v68, v68
	v_rcp_f32_e32 v69, v69
	s_nop 0
	v_pk_mul_f32 v[66:67], v[66:67], v[68:69]
	s_nop 0
	v_pk_mul_f32 v[66:67], v[70:71], v[66:67]
	s_nop 0
	v_cvt_pk_bf16_f32 v65, v66, v67
	v_mov_b32_e32 v236, v64
	v_mov_b32_e32 v237, v65
	s_nop 1
	v_permlane32_swap_b32_e32 v234, v236
	v_permlane32_swap_b32_e32 v235, v237
	global_store_dwordx4 v[240:241], v[234:237], off offset:32
; __device__ __forceinline__ int ltid() { int t = threadIdx.x; asm volatile("" : "+v"(t)); return t; }
; __device__ __forceinline__ float sigm(float x) { return __builtin_amdgcn_rcpf(1.f + __builtin_amdgcn_exp2f(-LOG2E * x)); }
; __device__ __forceinline__ void epi_swiglu(const f32x16 (&acc)[2][2], int nbase, int tbase, int M, const float* ss, u16* ACT) {
;   const int lane = ltid() & 63, l32 = lane & 31, h = lane >> 5;
;   const int cb = (nbase >> 6) * 32;
; #pragma unroll
;   for (int tb = 0; tb < 2; ++tb) {
;     const int tok = tbase + tb * 32 + l32;
;     if (tok < M) {
;       const float rs = rsqrtf(ss[tok] * (1.f / 1024.f) + EPSN);
;       u16* dst = ACT + (size_t)tok * FFD + cb + 4 * h;
; #pragma unroll
;       for (int i = 0; i < 4; ++i) {
;         float o[4];
; #pragma unroll
;         for (int j = 0; j < 4; ++j) {
;           const float g = acc[0][tb][4 * i + j] * rs, u = acc[1][tb][4 * i + j] * rs;
;           o[j] = g * sigm(g) * u;
;         }
;         *(u32x2*)(dst + 8 * i) = (u32x2){pk_bf16(o[0], o[1]), pk_bf16(o[2], o[3])};
;       }
;     }
;   }
; }
.LBB0_97:
	s_or_b64 exec, exec, s[34:35]
	v_mov_b32_e32 v64, v204
	s_movk_i32 s0, 0x80
	v_and_b32_e32 v65, 31, v64
	v_lshrrev_b32_e32 v64, 2, v64
	v_add3_u32 v66, v155, v65, s0
	v_and_b32_e32 v160, 8, v64
	v_lshl_add_u64 v[64:65], v[144:145], 0, v[160:161]
	v_cmp_gt_i32_e64 s[40:41], s62, v66
	v_ashrrev_i32_e32 v67, 31, v66
	s_and_saveexec_b64 s[34:35], s[40:41]
	s_cbranch_execz .LBB0_99
	v_lshl_add_u64 v[68:69], v[66:67], 2, s[44:45]
	global_load_dword v68, v[68:69], off
	s_waitcnt vmcnt(0)
	v_fmamk_f32 v68, v68, 0x3a800000, v205
	v_cmp_gt_f32_e64 s[40:41], s21, v68
	v_mul_f32_e32 v69, 0x4b800000, v68
	s_nop 0
	v_cndmask_b32_e64 v68, v68, v69, s[40:41]
	v_rsq_f32_e32 v68, v68
	s_nop 0
	v_mul_f32_e32 v69, 0x45800000, v68
	v_cndmask_b32_e64 v70, v68, v69, s[40:41]
	v_pk_mul_f32 v[48:49], v[48:49], v[70:71] op_sel_hi:[1,0]
	v_mad_i64_i32 v[68:69], s[0:1], v66, s56, v[64:65]
	v_mul_f32_e32 v71, 0xbfb8aa3b, v48
	v_exp_f32_e32 v71, v71
	s_nop 0
	v_add_f32_e32 v71, 1.0, v71
	v_rcp_f32_e32 v72, v71
	v_pk_mul_f32 v[32:33], v[32:33], v[70:71] op_sel_hi:[1,0]
	v_mul_f32_e32 v71, 0xbfb8aa3b, v49
	v_exp_f32_e32 v71, v71
	s_nop 0
	v_add_f32_e32 v71, 1.0, v71
	v_rcp_f32_e32 v73, v71
	v_pk_mul_f32 v[34:35], v[34:35], v[70:71] op_sel_hi:[1,0]
	v_pk_mul_f32 v[36:37], v[36:37], v[70:71] op_sel_hi:[1,0]
	v_pk_mul_f32 v[38:39], v[38:39], v[70:71] op_sel_hi:[1,0]
	v_pk_mul_f32 v[48:49], v[48:49], v[72:73]
	s_nop 0
	v_pk_mul_f32 v[32:33], v[32:33], v[48:49]
	v_pk_mul_f32 v[48:49], v[50:51], v[70:71] op_sel_hi:[1,0]
	v_cvt_pk_bf16_f32 v32, v32, v33
	v_mul_f32_e32 v50, 0xbfb8aa3b, v48
	v_mul_f32_e32 v51, 0xbfb8aa3b, v49
	v_exp_f32_e32 v50, v50
	v_exp_f32_e32 v51, v51
	v_add_f32_e32 v50, 1.0, v50
	v_add_f32_e32 v51, 1.0, v51
	v_rcp_f32_e32 v50, v50
	v_rcp_f32_e32 v51, v51
	s_nop 0
	v_pk_mul_f32 v[48:49], v[48:49], v[50:51]
	s_nop 0
	v_pk_mul_f32 v[34:35], v[34:35], v[48:49]
	s_nop 0
	v_cvt_pk_bf16_f32 v33, v34, v35
	v_mov_b32_e32 v222, v32
	v_mov_b32_e32 v223, v33
	v_pk_mul_f32 v[32:33], v[52:53], v[70:71] op_sel_hi:[1,0]
	s_nop 0
	v_mul_f32_e32 v34, 0xbfb8aa3b, v32
	v_mul_f32_e32 v35, 0xbfb8aa3b, v33
	v_exp_f32_e32 v34, v34
	v_exp_f32_e32 v35, v35
	v_add_f32_e32 v34, 1.0, v34
	v_add_f32_e32 v35, 1.0, v35
	v_rcp_f32_e32 v34, v34
	v_rcp_f32_e32 v35, v35
	s_nop 0
	v_pk_mul_f32 v[32:33], v[32:33], v[34:35]
	v_pk_mul_f32 v[34:35], v[54:55], v[70:71] op_sel_hi:[1,0]
	v_pk_mul_f32 v[32:33], v[36:37], v[32:33]
	v_mul_f32_e32 v36, 0xbfb8aa3b, v34
	v_mul_f32_e32 v37, 0xbfb8aa3b, v35
	v_exp_f32_e32 v36, v36
	v_exp_f32_e32 v37, v37
	v_cvt_pk_bf16_f32 v32, v32, v33
	v_add_f32_e32 v36, 1.0, v36
	v_add_f32_e32 v37, 1.0, v37
	v_rcp_f32_e32 v36, v36
	v_rcp_f32_e32 v37, v37
	s_nop 0
	v_pk_mul_f32 v[34:35], v[34:35], v[36:37]
	s_nop 0
	v_pk_mul_f32 v[34:35], v[38:39], v[34:35]
	v_pk_mul_f32 v[36:37], v[40:41], v[70:71] op_sel_hi:[1,0]
	v_cvt_pk_bf16_f32 v33, v34, v35
	v_mov_b32_e32 v224, v32
	v_mov_b32_e32 v225, v33
	v_lshrrev_b32_e32 v238, 2, v204
	v_and_b32_e32 v238, 8, v238
	v_mov_b32_e32 v239, 0
	v_lshl_add_u64 v[240:241], v[68:69], 0, v[238:239]
	v_permlane32_swap_b32_e32 v222, v224
	v_permlane32_swap_b32_e32 v223, v225
	global_store_dwordx4 v[240:241], v[222:225], off
	v_pk_mul_f32 v[32:33], v[56:57], v[70:71] op_sel_hi:[1,0]
	v_pk_mul_f32 v[38:39], v[42:43], v[70:71] op_sel_hi:[1,0]
	v_mul_f32_e32 v34, 0xbfb8aa3b, v32
	v_mul_f32_e32 v35, 0xbfb8aa3b, v33
	v_exp_f32_e32 v34, v34
	v_exp_f32_e32 v35, v35
	v_add_f32_e32 v34, 1.0, v34
	v_add_f32_e32 v35, 1.0, v35
	v_rcp_f32_e32 v34, v34
	v_rcp_f32_e32 v35, v35
	s_nop 0
	v_pk_mul_f32 v[32:33], v[32:33], v[34:35]
	v_pk_mul_f32 v[34:35], v[58:59], v[70:71] op_sel_hi:[1,0]
	v_pk_mul_f32 v[32:33], v[36:37], v[32:33]
	v_mul_f32_e32 v36, 0xbfb8aa3b, v34
	v_mul_f32_e32 v37, 0xbfb8aa3b, v35
	v_exp_f32_e32 v36, v36
	v_exp_f32_e32 v37, v37
	v_cvt_pk_bf16_f32 v32, v32, v33
	v_add_f32_e32 v36, 1.0, v36
	v_add_f32_e32 v37, 1.0, v37
	v_rcp_f32_e32 v36, v36
	v_rcp_f32_e32 v37, v37
	s_nop 0
	v_pk_mul_f32 v[34:35], v[34:35], v[36:37]
	s_nop 0
	v_pk_mul_f32 v[34:35], v[38:39], v[34:35]
	v_pk_mul_f32 v[36:37], v[44:45], v[70:71] op_sel_hi:[1,0]
	v_cvt_pk_bf16_f32 v33, v34, v35
	v_mov_b32_e32 v226, v32
	v_mov_b32_e32 v227, v33
	v_pk_mul_f32 v[32:33], v[60:61], v[70:71] op_sel_hi:[1,0]
	v_pk_mul_f32 v[38:39], v[46:47], v[70:71] op_sel_hi:[1,0]
	v_mul_f32_e32 v34, 0xbfb8aa3b, v32
	v_mul_f32_e32 v35, 0xbfb8aa3b, v33
	v_exp_f32_e32 v34, v34
	v_exp_f32_e32 v35, v35
	v_add_f32_e32 v34, 1.0, v34
	v_add_f32_e32 v35, 1.0, v35
	v_rcp_f32_e32 v34, v34
	v_rcp_f32_e32 v35, v35
	s_nop 0
	v_pk_mul_f32 v[32:33], v[32:33], v[34:35]
	v_pk_mul_f32 v[34:35], v[62:63], v[70:71] op_sel_hi:[1,0]
	v_pk_mul_f32 v[32:33], v[36:37], v[32:33]
	v_mul_f32_e32 v36, 0xbfb8aa3b, v34
	v_mul_f32_e32 v37, 0xbfb8aa3b, v35
	v_exp_f32_e32 v36, v36
	v_exp_f32_e32 v37, v37
	v_cvt_pk_bf16_f32 v32, v32, v33
	v_add_f32_e32 v36, 1.0, v36
	v_add_f32_e32 v37, 1.0, v37
	v_rcp_f32_e32 v36, v36
	v_rcp_f32_e32 v37, v37
	s_nop 0
	v_pk_mul_f32 v[34:35], v[34:35], v[36:37]
	s_nop 0
	v_pk_mul_f32 v[34:35], v[38:39], v[34:35]
	s_nop 0
	v_cvt_pk_bf16_f32 v33, v34, v35
	v_mov_b32_e32 v228, v32
	v_mov_b32_e32 v229, v33
	s_nop 1
	v_permlane32_swap_b32_e32 v226, v228
	v_permlane32_swap_b32_e32 v227, v229
	global_store_dwordx4 v[240:241], v[226:229], off offset:32
; __device__ __forceinline__ float sigm(float x) { return __builtin_amdgcn_rcpf(1.f + __builtin_amdgcn_exp2f(-LOG2E * x)); }
; __device__ __forceinline__ void epi_swiglu(const f32x16 (&acc)[2][2], int nbase, int tbase, int M, const float* ss, u16* ACT) {
;     ...
;   for (int tb = 0; tb < 2; ++tb) {
;     const int tok = tbase + tb * 32 + l32;
;     if (tok < M) {
;       const float rs = rsqrtf(ss[tok] * (1.f / 1024.f) + EPSN);
;       u16* dst = ACT + (size_t)tok * FFD + cb + 4 * h;
; #pragma unroll
;       for (int i = 0; i < 4; ++i) {
;         float o[4];
; #pragma unroll
;         for (int j = 0; j < 4; ++j) {
;           const float g = acc[0][tb][4 * i + j] * rs, u = acc[1][tb][4 * i + j] * rs;
;           o[j] = g * sigm(g) * u;
;         }
;         *(u32x2*)(dst + 8 * i) = (u32x2){pk_bf16(o[0], o[1]), pk_bf16(o[2], o[3])};
;       }
;     }
;   }
.LBB0_99:
	s_or_b64 exec, exec, s[34:35]
	v_or_b32_e32 v32, 32, v66
	v_cmp_gt_i32_e64 s[40:41], s62, v32
	s_and_saveexec_b64 s[34:35], s[40:41]
	s_cbranch_execz .LBB0_84
	v_lshl_add_u64 v[34:35], v[66:67], 2, s[44:45]
	global_load_dword v33, v[34:35], off offset:128
	s_waitcnt vmcnt(0)
	v_fmamk_f32 v33, v33, 0x3a800000, v205
	v_cmp_gt_f32_e64 s[40:41], s21, v33
	v_mul_f32_e32 v34, 0x4b800000, v33
	s_nop 0
	v_cndmask_b32_e64 v33, v33, v34, s[40:41]
	v_rsq_f32_e32 v33, v33
	s_nop 0
	v_mul_f32_e32 v34, 0x45800000, v33
	v_cndmask_b32_e64 v34, v33, v34, s[40:41]
	v_pk_mul_f32 v[16:17], v[16:17], v[34:35] op_sel_hi:[1,0]
	v_mad_i64_i32 v[32:33], s[0:1], v32, s56, v[64:65]
	v_mul_f32_e32 v35, 0xbfb8aa3b, v16
	v_exp_f32_e32 v35, v35
	s_nop 0
	v_add_f32_e32 v35, 1.0, v35
	v_rcp_f32_e32 v36, v35
	v_pk_mul_f32 v[0:1], v[0:1], v[34:35] op_sel_hi:[1,0]
	v_mul_f32_e32 v35, 0xbfb8aa3b, v17
	v_exp_f32_e32 v35, v35
	s_nop 0
	v_add_f32_e32 v35, 1.0, v35
	v_rcp_f32_e32 v37, v35
	v_pk_mul_f32 v[2:3], v[2:3], v[34:35] op_sel_hi:[1,0]
	v_pk_mul_f32 v[4:5], v[4:5], v[34:35] op_sel_hi:[1,0]
	v_pk_mul_f32 v[6:7], v[6:7], v[34:35] op_sel_hi:[1,0]
	v_pk_mul_f32 v[16:17], v[16:17], v[36:37]
	s_nop 0
	v_pk_mul_f32 v[0:1], v[0:1], v[16:17]
	v_pk_mul_f32 v[16:17], v[18:19], v[34:35] op_sel_hi:[1,0]
	v_cvt_pk_bf16_f32 v0, v0, v1
	v_mul_f32_e32 v18, 0xbfb8aa3b, v16
	v_mul_f32_e32 v19, 0xbfb8aa3b, v17
	v_exp_f32_e32 v18, v18
	v_exp_f32_e32 v19, v19
	v_add_f32_e32 v18, 1.0, v18
	v_add_f32_e32 v19, 1.0, v19
	v_rcp_f32_e32 v18, v18
	v_rcp_f32_e32 v19, v19
	s_nop 0
	v_pk_mul_f32 v[16:17], v[16:17], v[18:19]
	s_nop 0
	v_pk_mul_f32 v[2:3], v[2:3], v[16:17]
	s_nop 0
	v_cvt_pk_bf16_f32 v1, v2, v3
	v_mov_b32_e32 v230, v0
	v_mov_b32_e32 v231, v1
	v_pk_mul_f32 v[0:1], v[20:21], v[34:35] op_sel_hi:[1,0]
	s_nop 0
	v_mul_f32_e32 v2, 0xbfb8aa3b, v0
	v_mul_f32_e32 v3, 0xbfb8aa3b, v1
	v_exp_f32_e32 v2, v2
	v_exp_f32_e32 v3, v3
	v_add_f32_e32 v2, 1.0, v2
	v_add_f32_e32 v3, 1.0, v3
	v_rcp_f32_e32 v2, v2
	v_rcp_f32_e32 v3, v3
	s_nop 0
	v_pk_mul_f32 v[0:1], v[0:1], v[2:3]
	v_pk_mul_f32 v[2:3], v[22:23], v[34:35] op_sel_hi:[1,0]
	v_pk_mul_f32 v[0:1], v[4:5], v[0:1]
	v_mul_f32_e32 v4, 0xbfb8aa3b, v2
	v_mul_f32_e32 v5, 0xbfb8aa3b, v3
	v_exp_f32_e32 v4, v4
	v_exp_f32_e32 v5, v5
	v_cvt_pk_bf16_f32 v0, v0, v1
	v_add_f32_e32 v4, 1.0, v4
	v_add_f32_e32 v5, 1.0, v5
	v_rcp_f32_e32 v4, v4
	v_rcp_f32_e32 v5, v5
	s_nop 0
	v_pk_mul_f32 v[2:3], v[2:3], v[4:5]
	s_nop 0
	v_pk_mul_f32 v[2:3], v[6:7], v[2:3]
	v_pk_mul_f32 v[4:5], v[8:9], v[34:35] op_sel_hi:[1,0]
	v_cvt_pk_bf16_f32 v1, v2, v3
	v_mov_b32_e32 v232, v0
	v_mov_b32_e32 v233, v1
	v_lshrrev_b32_e32 v238, 2, v204
	v_and_b32_e32 v238, 8, v238
	v_mov_b32_e32 v239, 0
	v_lshl_add_u64 v[240:241], v[32:33], 0, v[238:239]
	v_permlane32_swap_b32_e32 v230, v232
	v_permlane32_swap_b32_e32 v231, v233
	global_store_dwordx4 v[240:241], v[230:233], off
	v_pk_mul_f32 v[0:1], v[24:25], v[34:35] op_sel_hi:[1,0]
	v_pk_mul_f32 v[6:7], v[10:11], v[34:35] op_sel_hi:[1,0]
	v_mul_f32_e32 v2, 0xbfb8aa3b, v0
	v_mul_f32_e32 v3, 0xbfb8aa3b, v1
	v_exp_f32_e32 v2, v2
	v_exp_f32_e32 v3, v3
	v_add_f32_e32 v2, 1.0, v2
	v_add_f32_e32 v3, 1.0, v3
	v_rcp_f32_e32 v2, v2
	v_rcp_f32_e32 v3, v3
	s_nop 0
	v_pk_mul_f32 v[0:1], v[0:1], v[2:3]
	v_pk_mul_f32 v[2:3], v[26:27], v[34:35] op_sel_hi:[1,0]
	v_pk_mul_f32 v[0:1], v[4:5], v[0:1]
	v_mul_f32_e32 v4, 0xbfb8aa3b, v2
	v_mul_f32_e32 v5, 0xbfb8aa3b, v3
	v_exp_f32_e32 v4, v4
	v_exp_f32_e32 v5, v5
	v_cvt_pk_bf16_f32 v0, v0, v1
	v_add_f32_e32 v4, 1.0, v4
	v_add_f32_e32 v5, 1.0, v5
	v_rcp_f32_e32 v4, v4
	v_rcp_f32_e32 v5, v5
	s_nop 0
	v_pk_mul_f32 v[2:3], v[2:3], v[4:5]
	s_nop 0
	v_pk_mul_f32 v[2:3], v[6:7], v[2:3]
	v_pk_mul_f32 v[4:5], v[12:13], v[34:35] op_sel_hi:[1,0]
	v_cvt_pk_bf16_f32 v1, v2, v3
	v_mov_b32_e32 v234, v0
	v_mov_b32_e32 v235, v1
	v_pk_mul_f32 v[0:1], v[28:29], v[34:35] op_sel_hi:[1,0]
	v_pk_mul_f32 v[6:7], v[14:15], v[34:35] op_sel_hi:[1,0]
	v_mul_f32_e32 v2, 0xbfb8aa3b, v0
	v_mul_f32_e32 v3, 0xbfb8aa3b, v1
	v_exp_f32_e32 v2, v2
	v_exp_f32_e32 v3, v3
	v_add_f32_e32 v2, 1.0, v2
	v_add_f32_e32 v3, 1.0, v3
	v_rcp_f32_e32 v2, v2
	v_rcp_f32_e32 v3, v3
	s_nop 0
	v_pk_mul_f32 v[0:1], v[0:1], v[2:3]
	v_pk_mul_f32 v[2:3], v[30:31], v[34:35] op_sel_hi:[1,0]
	v_pk_mul_f32 v[0:1], v[4:5], v[0:1]
	v_mul_f32_e32 v4, 0xbfb8aa3b, v2
	v_mul_f32_e32 v5, 0xbfb8aa3b, v3
	v_exp_f32_e32 v4, v4
	v_exp_f32_e32 v5, v5
	v_cvt_pk_bf16_f32 v0, v0, v1
	v_add_f32_e32 v4, 1.0, v4
	v_add_f32_e32 v5, 1.0, v5
	v_rcp_f32_e32 v4, v4
	v_rcp_f32_e32 v5, v5
	s_nop 0
	v_pk_mul_f32 v[2:3], v[2:3], v[4:5]
	s_nop 0
	v_pk_mul_f32 v[2:3], v[6:7], v[2:3]
	s_nop 0
	v_cvt_pk_bf16_f32 v1, v2, v3
	v_mov_b32_e32 v236, v0
	v_mov_b32_e32 v237, v1
	s_nop 1
	v_permlane32_swap_b32_e32 v234, v236
	v_permlane32_swap_b32_e32 v235, v237
	global_store_dwordx4 v[240:241], v[234:237], off offset:32
	s_branch .LBB0_84

; __device__ __forceinline__ float bf_lo(unsigned u) { return __uint_as_float(u << 16); }
; __device__ __forceinline__ float bf_hi(unsigned u) { return __uint_as_float(u & 0xffff0000u); }
; template <int MODE>
; __device__ __forceinline__ void epi_resid(const f32x16 (&acc)[2][2], int nbase, int tbase, CP& p, const Grp& G) {
;     ...
;   for (int tb = 0; tb < 2; ++tb) {
;     const int tok = tbase + tb * 32 + l32;
;     const bool valid = tok < G.Mx;
;     float sq = 0.f;
;     if (valid) {
;       float* hp = p.H + (size_t)tok * 1024;
;       u16* hb = p.HB + (size_t)tok * 1024;
;       const float* rp = G.x + (size_t)tok * 1024;
; #pragma unroll
;       for (int nb = 0; nb < 2; ++nb)
; #pragma unroll
;         for (int i = 0; i < 4; ++i) {
;           const int n = nbase + nb * 32 + 8 * i + 4 * h;
;           f32x4 r;
;           if (MODE == 0) r = *(const f32x4*)(rp + n);
;           else { const u32x2 rb = *(const u32x2*)(hb + n); r = (f32x4){bf_lo(rb.x), bf_hi(rb.x), bf_lo(rb.y), bf_hi(rb.y)}; }
;           f32x4 v;
;           v.x = r.x + scale * acc[nb][tb][4 * i + 0];
;           v.y = r.y + scale * acc[nb][tb][4 * i + 1];
;           v.z = r.z + scale * acc[nb][tb][4 * i + 2];
;           v.w = r.w + scale * acc[nb][tb][4 * i + 3];
;           sq += v.x * v.x + v.y * v.y + v.z * v.z + v.w * v.w;
;           if (MODE == 2) *(f32x4*)(hp + n) = v;
;           else *(u32x2*)(hb + n) = (u32x2){pk_bf16(v.x, v.y), pk_bf16(v.z, v.w)};
;         }
;     }
;     sq += __shfl_xor(sq, 32);
;     if (valid && h == 0) atomicAdd(ssout + tok, sq);
;   }
.LBB0_118:
	s_or_b64 exec, exec, s[6:7]
	v_mov_b32_e32 v144, v204
	v_lshl_or_b32 v152, v169, 7, v166
	v_lshl_add_u32 v153, v168, 8, v167
	v_mov_b32_e32 v155, 0
	v_bfe_u32 v154, v144, 5, 1
	v_and_or_b32 v144, v144, 31, v153
	v_lshl_or_b32 v146, v154, 2, v152
	v_cmp_gt_i32_e64 s[42:43], s62, v144
	v_ashrrev_i32_e32 v145, 31, v144
	v_ashrrev_i32_e32 v147, 31, v146
	s_and_saveexec_b64 s[34:35], s[42:43]
	s_cbranch_execz .LBB0_120
	v_lshlrev_b64 v[148:149], 11, v[144:145]
	v_lshl_add_u64 v[148:149], s[46:47], 0, v[148:149]
	v_lshl_add_u64 v[148:149], v[146:147], 1, v[148:149]
	global_load_dwordx2 v[178:179], v[148:149], off
	global_load_dwordx2 v[180:181], v[148:149], off offset:16
	global_load_dwordx2 v[182:183], v[148:149], off offset:32
	global_load_dwordx2 v[184:185], v[148:149], off offset:48
	global_load_dwordx2 v[186:187], v[148:149], off offset:64
	global_load_dwordx2 v[188:189], v[148:149], off offset:80
	global_load_dwordx2 v[190:191], v[148:149], off offset:96
	global_load_dwordx2 v[192:193], v[148:149], off offset:112
	s_nop 0
	v_mov_b32_e32 v174, v112
	v_mov_b32_e32 v175, v116
	v_mov_b32_e32 v116, v113
	v_mov_b32_e32 v176, v114
	v_mov_b32_e32 v177, v118
	v_mov_b32_e32 v118, v115
	s_waitcnt vmcnt(7)
	v_lshlrev_b32_e32 v172, 16, v178
	s_waitcnt vmcnt(6)
	v_lshlrev_b32_e32 v173, 16, v180
	v_pk_add_f32 v[172:173], v[174:175], v[172:173]
	v_and_b32_e32 v175, 0xffff0000, v180
	v_and_b32_e32 v174, 0xffff0000, v178
	v_pk_add_f32 v[116:117], v[116:117], v[174:175]
	v_lshlrev_b32_e32 v175, 16, v181
	v_lshlrev_b32_e32 v174, 16, v179
	v_and_b32_e32 v171, 0xffff0000, v181
	v_and_b32_e32 v170, 0xffff0000, v179
	v_pk_add_f32 v[174:175], v[176:177], v[174:175]
	v_pk_add_f32 v[114:115], v[118:119], v[170:171]
	v_cvt_pk_bf16_f32 v112, v172, v116
	v_cvt_pk_bf16_f32 v113, v174, v114
	v_mov_b32_e32 v222, v112
	v_mov_b32_e32 v223, v113
	v_pk_mul_f32 v[112:113], v[116:117], v[116:117]
	s_nop 0
	v_pk_fma_f32 v[112:113], v[172:173], v[172:173], v[112:113]
	s_nop 0
	v_pk_fma_f32 v[112:113], v[174:175], v[174:175], v[112:113]
	s_nop 0
	v_pk_fma_f32 v[112:113], v[114:115], v[114:115], v[112:113]
	v_cvt_pk_bf16_f32 v114, v173, v117
	v_cvt_pk_bf16_f32 v115, v175, v115
	v_mov_b32_e32 v224, v114
	v_mov_b32_e32 v225, v115
	v_lshrrev_b32_e32 v238, 2, v204
	v_and_b32_e32 v238, 8, v238
	v_mov_b32_e32 v239, 0
	v_lshl_add_u64 v[240:241], v[148:149], 0, v[238:239]
	v_permlane32_swap_b32_e32 v222, v224
	v_permlane32_swap_b32_e32 v223, v225
	global_store_dwordx4 v[240:241], v[222:225], off
	s_nop 0
	s_nop 0
	s_nop 0
	s_waitcnt vmcnt(6)
	v_lshlrev_b32_e32 v118, 16, v182
	s_waitcnt vmcnt(5)
	v_lshlrev_b32_e32 v119, 16, v184
	v_and_b32_e32 v169, 0xffff0000, v184
	v_and_b32_e32 v168, 0xffff0000, v182
	v_lshlrev_b32_e32 v170, 16, v183
	v_and_b32_e32 v116, 0xffff0000, v183
	v_mov_b32_e32 v114, v120
	v_mov_b32_e32 v115, v124
	v_mov_b32_e32 v124, v121
	v_lshlrev_b32_e32 v171, 16, v185
	v_pk_add_f32 v[118:119], v[114:115], v[118:119]
	v_pk_add_f32 v[120:121], v[124:125], v[168:169]
	v_mov_b32_e32 v114, v122
	v_mov_b32_e32 v115, v126
	v_pk_add_f32 v[124:125], v[114:115], v[170:171]
	v_pk_mul_f32 v[114:115], v[120:121], v[120:121]
	v_and_b32_e32 v117, 0xffff0000, v185
	v_mov_b32_e32 v126, v123
	v_pk_fma_f32 v[114:115], v[118:119], v[118:119], v[114:115]
	v_pk_add_f32 v[116:117], v[126:127], v[116:117]
	v_pk_fma_f32 v[114:115], v[124:125], v[124:125], v[114:115]
	v_cvt_pk_bf16_f32 v122, v118, v120
	v_pk_fma_f32 v[114:115], v[116:117], v[116:117], v[114:115]
	v_cvt_pk_bf16_f32 v123, v124, v116
	v_cvt_pk_bf16_f32 v116, v119, v121
	v_cvt_pk_bf16_f32 v117, v125, v117
	v_mov_b32_e32 v226, v122
	v_mov_b32_e32 v227, v123
	v_mov_b32_e32 v228, v116
	v_mov_b32_e32 v229, v117
	s_nop 1
	v_permlane32_swap_b32_e32 v226, v228
	v_permlane32_swap_b32_e32 v227, v229
	global_store_dwordx4 v[240:241], v[226:229], off offset:32
	s_nop 0
	s_nop 0
	s_nop 0
	s_waitcnt vmcnt(5)
	v_and_b32_e32 v122, 0xffff0000, v186
	s_waitcnt vmcnt(4)
	v_lshlrev_b32_e32 v121, 16, v188
	v_and_b32_e32 v123, 0xffff0000, v188
	v_lshlrev_b32_e32 v124, 16, v187
	v_and_b32_e32 v118, 0xffff0000, v187
	v_mov_b32_e32 v117, v100
	v_mov_b32_e32 v100, v97
	v_lshlrev_b32_e32 v120, 16, v186
	v_lshlrev_b32_e32 v125, 16, v189
	v_mov_b32_e32 v116, v96
	v_pk_add_f32 v[100:101], v[100:101], v[122:123]
	v_mov_b32_e32 v96, v98
	v_mov_b32_e32 v97, v102
	v_pk_add_f32 v[116:117], v[116:117], v[120:121]
	v_pk_add_f32 v[120:121], v[96:97], v[124:125]
	v_pk_mul_f32 v[96:97], v[100:101], v[100:101]
	v_and_b32_e32 v119, 0xffff0000, v189
	v_mov_b32_e32 v102, v99
	v_pk_fma_f32 v[96:97], v[116:117], v[116:117], v[96:97]
	v_pk_add_f32 v[98:99], v[102:103], v[118:119]
	v_pk_fma_f32 v[96:97], v[120:121], v[120:121], v[96:97]
	v_cvt_pk_bf16_f32 v102, v116, v100
	v_pk_fma_f32 v[96:97], v[98:99], v[98:99], v[96:97]
	v_cvt_pk_bf16_f32 v103, v120, v98
	v_cvt_pk_bf16_f32 v98, v117, v101
	v_cvt_pk_bf16_f32 v99, v121, v99
	v_mov_b32_e32 v230, v102
	v_mov_b32_e32 v231, v103
	v_mov_b32_e32 v232, v98
	v_mov_b32_e32 v233, v99
	s_nop 1
	v_permlane32_swap_b32_e32 v230, v232
	v_permlane32_swap_b32_e32 v231, v233
	global_store_dwordx4 v[240:241], v[230:233], off offset:64
	s_nop 0
	s_nop 0
	s_nop 0
	s_waitcnt vmcnt(4)
	v_lshlrev_b32_e32 v102, 16, v190
	s_waitcnt vmcnt(3)
	v_lshlrev_b32_e32 v103, 16, v192
	v_and_b32_e32 v117, 0xffff0000, v192
	v_and_b32_e32 v116, 0xffff0000, v190
	v_lshlrev_b32_e32 v118, 16, v191
	v_and_b32_e32 v100, 0xffff0000, v191
	v_mov_b32_e32 v98, v104
	v_mov_b32_e32 v99, v108
	v_mov_b32_e32 v108, v105
	v_pk_add_f32 v[98:99], v[98:99], v[102:103]
	v_pk_add_f32 v[102:103], v[108:109], v[116:117]
	v_mov_b32_e32 v104, v106
	v_mov_b32_e32 v105, v110
	v_mov_b32_e32 v110, v107
	v_pk_mul_f32 v[106:107], v[102:103], v[102:103]
	v_cvt_pk_bf16_f32 v108, v98, v102
	v_pk_fma_f32 v[106:107], v[98:99], v[98:99], v[106:107]
	v_add_f32_e32 v98, v112, v113
	v_lshlrev_b32_e32 v119, 16, v193
	v_add_f32_e32 v98, v98, v114
	v_and_b32_e32 v101, 0xffff0000, v193
	v_pk_add_f32 v[104:105], v[104:105], v[118:119]
	v_add_f32_e32 v98, v98, v115
	v_pk_add_f32 v[100:101], v[110:111], v[100:101]
	v_pk_fma_f32 v[106:107], v[104:105], v[104:105], v[106:107]
	v_add_f32_e32 v96, v98, v96
	v_pk_fma_f32 v[106:107], v[100:101], v[100:101], v[106:107]
	v_add_f32_e32 v96, v96, v97
	v_add_f32_e32 v96, v96, v106
	v_cvt_pk_bf16_f32 v109, v104, v100
	v_add_f32_e32 v155, v96, v107
	v_cvt_pk_bf16_f32 v96, v99, v103
	v_cvt_pk_bf16_f32 v97, v105, v101
	v_mov_b32_e32 v234, v108
	v_mov_b32_e32 v235, v109
	v_mov_b32_e32 v236, v96
	v_mov_b32_e32 v237, v97
	s_nop 1
	v_permlane32_swap_b32_e32 v234, v236
	v_permlane32_swap_b32_e32 v235, v237
	global_store_dwordx4 v[240:241], v[234:237], off offset:96

; __device__ __forceinline__ float bf_lo(unsigned u) { return __uint_as_float(u << 16); }
; __device__ __forceinline__ float bf_hi(unsigned u) { return __uint_as_float(u & 0xffff0000u); }
; template <int MODE>
; __device__ __forceinline__ void epi_resid(const f32x16 (&acc)[2][2], int nbase, int tbase, CP& p, const Grp& G) {
;     ...
;   for (int tb = 0; tb < 2; ++tb) {
;     const int tok = tbase + tb * 32 + l32;
;     const bool valid = tok < G.Mx;
;     float sq = 0.f;
;     if (valid) {
;       float* hp = p.H + (size_t)tok * 1024;
;       u16* hb = p.HB + (size_t)tok * 1024;
;       const float* rp = G.x + (size_t)tok * 1024;
; #pragma unroll
;       for (int nb = 0; nb < 2; ++nb)
; #pragma unroll
;         for (int i = 0; i < 4; ++i) {
;           const int n = nbase + nb * 32 + 8 * i + 4 * h;
;           f32x4 r;
;           if (MODE == 0) r = *(const f32x4*)(rp + n);
;           else { const u32x2 rb = *(const u32x2*)(hb + n); r = (f32x4){bf_lo(rb.x), bf_hi(rb.x), bf_lo(rb.y), bf_hi(rb.y)}; }
;           f32x4 v;
;           v.x = r.x + scale * acc[nb][tb][4 * i + 0];
;           v.y = r.y + scale * acc[nb][tb][4 * i + 1];
;           v.z = r.z + scale * acc[nb][tb][4 * i + 2];
;           v.w = r.w + scale * acc[nb][tb][4 * i + 3];
;           sq += v.x * v.x + v.y * v.y + v.z * v.z + v.w * v.w;
;           if (MODE == 2) *(f32x4*)(hp + n) = v;
;           else *(u32x2*)(hb + n) = (u32x2){pk_bf16(v.x, v.y), pk_bf16(v.z, v.w)};
;         }
;     }
;     sq += __shfl_xor(sq, 32);
;     if (valid && h == 0) atomicAdd(ssout + tok, sq);
;   }
.LBB0_122:
	s_or_b64 exec, exec, s[0:1]
	s_waitcnt lgkmcnt(0)
	v_or_b32_e32 v96, 32, v144
	v_cmp_gt_i32_e64 s[42:43], s62, v96
	v_mov_b32_e32 v99, 0
	s_and_saveexec_b64 s[34:35], s[42:43]
	s_cbranch_execz .LBB0_124
	v_ashrrev_i32_e32 v97, 31, v96
	v_lshlrev_b64 v[96:97], 11, v[96:97]
	v_lshl_add_u64 v[96:97], s[46:47], 0, v[96:97]
	v_lshl_add_u64 v[96:97], v[146:147], 1, v[96:97]
	global_load_dwordx2 v[178:179], v[96:97], off
	global_load_dwordx2 v[180:181], v[96:97], off offset:16
	global_load_dwordx2 v[182:183], v[96:97], off offset:32
	global_load_dwordx2 v[184:185], v[96:97], off offset:48
	global_load_dwordx2 v[186:187], v[96:97], off offset:64
	global_load_dwordx2 v[188:189], v[96:97], off offset:80
	global_load_dwordx2 v[190:191], v[96:97], off offset:96
	global_load_dwordx2 v[192:193], v[96:97], off offset:112
	s_nop 0
	v_mov_b32_e32 v106, v80
	v_mov_b32_e32 v107, v84
	v_mov_b32_e32 v84, v81
	v_mov_b32_e32 v108, v82
	v_mov_b32_e32 v109, v86
	v_mov_b32_e32 v86, v83
	s_waitcnt vmcnt(7)
	v_lshlrev_b32_e32 v104, 16, v178
	s_waitcnt vmcnt(6)
	v_lshlrev_b32_e32 v105, 16, v180
	v_pk_add_f32 v[104:105], v[106:107], v[104:105]
	v_and_b32_e32 v107, 0xffff0000, v180
	v_and_b32_e32 v106, 0xffff0000, v178
	v_pk_add_f32 v[84:85], v[84:85], v[106:107]
	v_lshlrev_b32_e32 v107, 16, v181
	v_lshlrev_b32_e32 v106, 16, v179
	v_and_b32_e32 v103, 0xffff0000, v181
	v_and_b32_e32 v102, 0xffff0000, v179
	v_pk_add_f32 v[106:107], v[108:109], v[106:107]
	v_pk_add_f32 v[82:83], v[86:87], v[102:103]
	v_cvt_pk_bf16_f32 v80, v104, v84
	v_cvt_pk_bf16_f32 v81, v106, v82
	v_mov_b32_e32 v222, v80
	v_mov_b32_e32 v223, v81
	v_pk_mul_f32 v[80:81], v[84:85], v[84:85]
	s_nop 0
	v_pk_fma_f32 v[80:81], v[104:105], v[104:105], v[80:81]
	s_nop 0
	v_pk_fma_f32 v[80:81], v[106:107], v[106:107], v[80:81]
	s_nop 0
	v_pk_fma_f32 v[80:81], v[82:83], v[82:83], v[80:81]
	v_cvt_pk_bf16_f32 v82, v105, v85
	v_cvt_pk_bf16_f32 v83, v107, v83
	v_mov_b32_e32 v224, v82
	v_mov_b32_e32 v225, v83
	v_lshrrev_b32_e32 v238, 2, v204
	v_and_b32_e32 v238, 8, v238
	v_mov_b32_e32 v239, 0
	v_lshl_add_u64 v[240:241], v[96:97], 0, v[238:239]
	v_permlane32_swap_b32_e32 v222, v224
	v_permlane32_swap_b32_e32 v223, v225
	global_store_dwordx4 v[240:241], v[222:225], off
	s_nop 0
	s_nop 0
	s_nop 0
	s_waitcnt vmcnt(6)
	v_lshlrev_b32_e32 v86, 16, v182
	s_waitcnt vmcnt(5)
	v_lshlrev_b32_e32 v87, 16, v184
	v_and_b32_e32 v101, 0xffff0000, v184
	v_and_b32_e32 v100, 0xffff0000, v182
	v_lshlrev_b32_e32 v102, 16, v183
	v_and_b32_e32 v84, 0xffff0000, v183
	v_mov_b32_e32 v82, v88
	v_mov_b32_e32 v83, v92
	v_mov_b32_e32 v92, v89
	v_lshlrev_b32_e32 v103, 16, v185
	v_pk_add_f32 v[86:87], v[82:83], v[86:87]
	v_pk_add_f32 v[88:89], v[92:93], v[100:101]
	v_mov_b32_e32 v82, v90
	v_mov_b32_e32 v83, v94
	v_pk_add_f32 v[92:93], v[82:83], v[102:103]
	v_pk_mul_f32 v[82:83], v[88:89], v[88:89]
	v_and_b32_e32 v85, 0xffff0000, v185
	v_mov_b32_e32 v94, v91
	v_pk_fma_f32 v[82:83], v[86:87], v[86:87], v[82:83]
	v_pk_add_f32 v[84:85], v[94:95], v[84:85]
	v_pk_fma_f32 v[82:83], v[92:93], v[92:93], v[82:83]
	v_cvt_pk_bf16_f32 v90, v86, v88
	v_pk_fma_f32 v[82:83], v[84:85], v[84:85], v[82:83]
	v_cvt_pk_bf16_f32 v91, v92, v84
	v_cvt_pk_bf16_f32 v84, v87, v89
	v_cvt_pk_bf16_f32 v85, v93, v85
	v_mov_b32_e32 v226, v90
	v_mov_b32_e32 v227, v91
	v_mov_b32_e32 v228, v84
	v_mov_b32_e32 v229, v85
	s_nop 1
	v_permlane32_swap_b32_e32 v226, v228
	v_permlane32_swap_b32_e32 v227, v229
	global_store_dwordx4 v[240:241], v[226:229], off offset:32
	s_nop 0
	s_nop 0
	s_nop 0
	s_waitcnt vmcnt(5)
	v_and_b32_e32 v90, 0xffff0000, v186
	s_waitcnt vmcnt(4)
	v_lshlrev_b32_e32 v89, 16, v188
	v_and_b32_e32 v91, 0xffff0000, v188
	v_lshlrev_b32_e32 v92, 16, v187
	v_and_b32_e32 v86, 0xffff0000, v187
	v_mov_b32_e32 v85, v68
	v_mov_b32_e32 v68, v65
	v_lshlrev_b32_e32 v88, 16, v186
	v_lshlrev_b32_e32 v93, 16, v189
	v_mov_b32_e32 v84, v64
	v_pk_add_f32 v[68:69], v[68:69], v[90:91]
	v_mov_b32_e32 v64, v66
	v_mov_b32_e32 v65, v70
	v_pk_add_f32 v[84:85], v[84:85], v[88:89]
	v_pk_add_f32 v[88:89], v[64:65], v[92:93]
	v_pk_mul_f32 v[64:65], v[68:69], v[68:69]
	v_and_b32_e32 v87, 0xffff0000, v189
	v_mov_b32_e32 v70, v67
	v_pk_fma_f32 v[64:65], v[84:85], v[84:85], v[64:65]
	v_pk_add_f32 v[66:67], v[70:71], v[86:87]
	v_pk_fma_f32 v[64:65], v[88:89], v[88:89], v[64:65]
	v_cvt_pk_bf16_f32 v70, v84, v68
	v_pk_fma_f32 v[64:65], v[66:67], v[66:67], v[64:65]
	v_cvt_pk_bf16_f32 v71, v88, v66
	v_cvt_pk_bf16_f32 v66, v85, v69
	v_cvt_pk_bf16_f32 v67, v89, v67
	v_mov_b32_e32 v230, v70
	v_mov_b32_e32 v231, v71
	v_mov_b32_e32 v232, v66
	v_mov_b32_e32 v233, v67
	s_nop 1
	v_permlane32_swap_b32_e32 v230, v232
	v_permlane32_swap_b32_e32 v231, v233
	global_store_dwordx4 v[240:241], v[230:233], off offset:64
	s_nop 0
	s_nop 0
	s_nop 0
	s_waitcnt vmcnt(4)
	v_lshlrev_b32_e32 v70, 16, v190
	s_waitcnt vmcnt(3)
	v_lshlrev_b32_e32 v71, 16, v192
	v_and_b32_e32 v85, 0xffff0000, v192
	v_and_b32_e32 v84, 0xffff0000, v190
	v_lshlrev_b32_e32 v86, 16, v191
	v_and_b32_e32 v68, 0xffff0000, v191
	v_mov_b32_e32 v66, v72
	v_mov_b32_e32 v67, v76
	v_mov_b32_e32 v76, v73
	v_pk_add_f32 v[66:67], v[66:67], v[70:71]
	v_pk_add_f32 v[70:71], v[76:77], v[84:85]
	v_mov_b32_e32 v72, v74
	v_mov_b32_e32 v73, v78
	v_mov_b32_e32 v78, v75
	v_pk_mul_f32 v[74:75], v[70:71], v[70:71]
	v_cvt_pk_bf16_f32 v76, v66, v70
	v_pk_fma_f32 v[74:75], v[66:67], v[66:67], v[74:75]
	v_add_f32_e32 v66, v80, v81
	v_lshlrev_b32_e32 v87, 16, v193
	v_add_f32_e32 v66, v66, v82
	v_and_b32_e32 v69, 0xffff0000, v193
	v_pk_add_f32 v[72:73], v[72:73], v[86:87]
	v_add_f32_e32 v66, v66, v83
	v_pk_add_f32 v[68:69], v[78:79], v[68:69]
	v_pk_fma_f32 v[74:75], v[72:73], v[72:73], v[74:75]
	v_add_f32_e32 v64, v66, v64
	v_pk_fma_f32 v[74:75], v[68:69], v[68:69], v[74:75]
	v_add_f32_e32 v64, v64, v65
	v_add_f32_e32 v64, v64, v74
	v_cvt_pk_bf16_f32 v77, v72, v68
	v_add_f32_e32 v99, v64, v75
	v_cvt_pk_bf16_f32 v64, v67, v71
	v_cvt_pk_bf16_f32 v65, v73, v69
	v_mov_b32_e32 v234, v76
	v_mov_b32_e32 v235, v77
	v_mov_b32_e32 v236, v64
	v_mov_b32_e32 v237, v65
	s_nop 1
	v_permlane32_swap_b32_e32 v234, v236
	v_permlane32_swap_b32_e32 v235, v237
	global_store_dwordx4 v[240:241], v[234:237], off offset:96

; __device__ __forceinline__ float bf_lo(unsigned u) { return __uint_as_float(u << 16); }
; __device__ __forceinline__ float bf_hi(unsigned u) { return __uint_as_float(u & 0xffff0000u); }
; template <int MODE>
; __device__ __forceinline__ void epi_resid(const f32x16 (&acc)[2][2], int nbase, int tbase, CP& p, const Grp& G) {
;     ...
;   for (int tb = 0; tb < 2; ++tb) {
;     const int tok = tbase + tb * 32 + l32;
;     const bool valid = tok < G.Mx;
;     float sq = 0.f;
;     if (valid) {
;       float* hp = p.H + (size_t)tok * 1024;
;       u16* hb = p.HB + (size_t)tok * 1024;
;       const float* rp = G.x + (size_t)tok * 1024;
; #pragma unroll
;       for (int nb = 0; nb < 2; ++nb)
; #pragma unroll
;         for (int i = 0; i < 4; ++i) {
;           const int n = nbase + nb * 32 + 8 * i + 4 * h;
;           f32x4 r;
;           if (MODE == 0) r = *(const f32x4*)(rp + n);
;           else { const u32x2 rb = *(const u32x2*)(hb + n); r = (f32x4){bf_lo(rb.x), bf_hi(rb.x), bf_lo(rb.y), bf_hi(rb.y)}; }
;           f32x4 v;
;           v.x = r.x + scale * acc[nb][tb][4 * i + 0];
;           v.y = r.y + scale * acc[nb][tb][4 * i + 1];
;           v.z = r.z + scale * acc[nb][tb][4 * i + 2];
;           v.w = r.w + scale * acc[nb][tb][4 * i + 3];
;           sq += v.x * v.x + v.y * v.y + v.z * v.z + v.w * v.w;
;           if (MODE == 2) *(f32x4*)(hp + n) = v;
;           else *(u32x2*)(hb + n) = (u32x2){pk_bf16(v.x, v.y), pk_bf16(v.z, v.w)};
;         }
;     }
;     sq += __shfl_xor(sq, 32);
;     if (valid && h == 0) atomicAdd(ssout + tok, sq);
;   }
.LBB0_126:
	s_or_b64 exec, exec, s[0:1]
	s_waitcnt lgkmcnt(0)
	v_mov_b32_e32 v64, v204
	s_movk_i32 s0, 0x80
	v_and_b32_e32 v65, 31, v64
	v_bfe_u32 v70, v64, 5, 1
	v_add3_u32 v64, v153, v65, s0
	v_lshl_or_b32 v66, v70, 2, v152
	v_cmp_gt_i32_e64 s[42:43], s62, v64
	v_mov_b32_e32 v71, 0
	v_ashrrev_i32_e32 v65, 31, v64
	v_ashrrev_i32_e32 v67, 31, v66
	s_and_saveexec_b64 s[34:35], s[42:43]
	s_cbranch_execz .LBB0_128
	v_lshlrev_b64 v[68:69], 11, v[64:65]
	v_lshl_add_u64 v[68:69], s[46:47], 0, v[68:69]
	v_lshl_add_u64 v[68:69], v[66:67], 1, v[68:69]
	global_load_dwordx2 v[178:179], v[68:69], off
	global_load_dwordx2 v[180:181], v[68:69], off offset:16
	global_load_dwordx2 v[182:183], v[68:69], off offset:32
	global_load_dwordx2 v[184:185], v[68:69], off offset:48
	global_load_dwordx2 v[186:187], v[68:69], off offset:64
	global_load_dwordx2 v[188:189], v[68:69], off offset:80
	global_load_dwordx2 v[190:191], v[68:69], off offset:96
	global_load_dwordx2 v[192:193], v[68:69], off offset:112
	s_nop 0
	v_mov_b32_e32 v78, v48
	v_mov_b32_e32 v79, v52
	v_mov_b32_e32 v52, v49
	v_mov_b32_e32 v80, v50
	v_mov_b32_e32 v81, v54
	v_mov_b32_e32 v54, v51
	s_waitcnt vmcnt(7)
	v_lshlrev_b32_e32 v76, 16, v178
	s_waitcnt vmcnt(6)
	v_lshlrev_b32_e32 v77, 16, v180
	v_pk_add_f32 v[76:77], v[78:79], v[76:77]
	v_and_b32_e32 v79, 0xffff0000, v180
	v_and_b32_e32 v78, 0xffff0000, v178
	v_pk_add_f32 v[52:53], v[52:53], v[78:79]
	v_lshlrev_b32_e32 v79, 16, v181
	v_lshlrev_b32_e32 v78, 16, v179
	v_and_b32_e32 v75, 0xffff0000, v181
	v_and_b32_e32 v74, 0xffff0000, v179
	v_pk_add_f32 v[78:79], v[80:81], v[78:79]
	v_pk_add_f32 v[50:51], v[54:55], v[74:75]
	v_cvt_pk_bf16_f32 v48, v76, v52
	v_cvt_pk_bf16_f32 v49, v78, v50
	v_mov_b32_e32 v222, v48
	v_mov_b32_e32 v223, v49
	v_pk_mul_f32 v[48:49], v[52:53], v[52:53]
	s_nop 0
	v_pk_fma_f32 v[48:49], v[76:77], v[76:77], v[48:49]
	s_nop 0
	v_pk_fma_f32 v[48:49], v[78:79], v[78:79], v[48:49]
	s_nop 0
	v_pk_fma_f32 v[48:49], v[50:51], v[50:51], v[48:49]
	v_cvt_pk_bf16_f32 v50, v77, v53
	v_cvt_pk_bf16_f32 v51, v79, v51
	v_mov_b32_e32 v224, v50
	v_mov_b32_e32 v225, v51
	v_lshrrev_b32_e32 v238, 2, v204
	v_and_b32_e32 v238, 8, v238
	v_mov_b32_e32 v239, 0
	v_lshl_add_u64 v[240:241], v[68:69], 0, v[238:239]
	v_permlane32_swap_b32_e32 v222, v224
	v_permlane32_swap_b32_e32 v223, v225
	global_store_dwordx4 v[240:241], v[222:225], off
	s_nop 0
	s_nop 0
	s_nop 0
	s_waitcnt vmcnt(6)
	v_lshlrev_b32_e32 v54, 16, v182
	s_waitcnt vmcnt(5)
	v_lshlrev_b32_e32 v55, 16, v184
	v_and_b32_e32 v73, 0xffff0000, v184
	v_and_b32_e32 v72, 0xffff0000, v182
	v_lshlrev_b32_e32 v74, 16, v183
	v_and_b32_e32 v52, 0xffff0000, v183
	v_mov_b32_e32 v50, v56
	v_mov_b32_e32 v51, v60
	v_mov_b32_e32 v60, v57
	v_lshlrev_b32_e32 v75, 16, v185
	v_pk_add_f32 v[54:55], v[50:51], v[54:55]
	v_pk_add_f32 v[56:57], v[60:61], v[72:73]
	v_mov_b32_e32 v50, v58
	v_mov_b32_e32 v51, v62
	v_pk_add_f32 v[60:61], v[50:51], v[74:75]
	v_pk_mul_f32 v[50:51], v[56:57], v[56:57]
	v_and_b32_e32 v53, 0xffff0000, v185
	v_mov_b32_e32 v62, v59
	v_pk_fma_f32 v[50:51], v[54:55], v[54:55], v[50:51]
	v_pk_add_f32 v[52:53], v[62:63], v[52:53]
	v_pk_fma_f32 v[50:51], v[60:61], v[60:61], v[50:51]
	v_cvt_pk_bf16_f32 v58, v54, v56
	v_pk_fma_f32 v[50:51], v[52:53], v[52:53], v[50:51]
	v_cvt_pk_bf16_f32 v59, v60, v52
	v_cvt_pk_bf16_f32 v52, v55, v57
	v_cvt_pk_bf16_f32 v53, v61, v53
	v_mov_b32_e32 v226, v58
	v_mov_b32_e32 v227, v59
	v_mov_b32_e32 v228, v52
	v_mov_b32_e32 v229, v53
	s_nop 1
	v_permlane32_swap_b32_e32 v226, v228
	v_permlane32_swap_b32_e32 v227, v229
	global_store_dwordx4 v[240:241], v[226:229], off offset:32
	s_nop 0
	s_nop 0
	s_nop 0
	s_waitcnt vmcnt(5)
	v_and_b32_e32 v58, 0xffff0000, v186
	s_waitcnt vmcnt(4)
	v_lshlrev_b32_e32 v57, 16, v188
	v_and_b32_e32 v59, 0xffff0000, v188
	v_lshlrev_b32_e32 v60, 16, v187
	v_and_b32_e32 v54, 0xffff0000, v187
	v_mov_b32_e32 v53, v36
	v_mov_b32_e32 v36, v33
	v_lshlrev_b32_e32 v56, 16, v186
	v_lshlrev_b32_e32 v61, 16, v189
	v_mov_b32_e32 v52, v32
	v_pk_add_f32 v[36:37], v[36:37], v[58:59]
	v_mov_b32_e32 v32, v34
	v_mov_b32_e32 v33, v38
	v_pk_add_f32 v[52:53], v[52:53], v[56:57]
	v_pk_add_f32 v[56:57], v[32:33], v[60:61]
	v_pk_mul_f32 v[32:33], v[36:37], v[36:37]
	v_and_b32_e32 v55, 0xffff0000, v189
	v_mov_b32_e32 v38, v35
	v_pk_fma_f32 v[32:33], v[52:53], v[52:53], v[32:33]
	v_pk_add_f32 v[34:35], v[38:39], v[54:55]
	v_pk_fma_f32 v[32:33], v[56:57], v[56:57], v[32:33]
	v_cvt_pk_bf16_f32 v38, v52, v36
	v_pk_fma_f32 v[32:33], v[34:35], v[34:35], v[32:33]
	v_cvt_pk_bf16_f32 v39, v56, v34
	v_cvt_pk_bf16_f32 v34, v53, v37
	v_cvt_pk_bf16_f32 v35, v57, v35
	v_mov_b32_e32 v230, v38
	v_mov_b32_e32 v231, v39
	v_mov_b32_e32 v232, v34
	v_mov_b32_e32 v233, v35
	s_nop 1
	v_permlane32_swap_b32_e32 v230, v232
	v_permlane32_swap_b32_e32 v231, v233
	global_store_dwordx4 v[240:241], v[230:233], off offset:64
	s_nop 0
	s_nop 0
	s_nop 0
	s_waitcnt vmcnt(4)
	v_lshlrev_b32_e32 v38, 16, v190
	s_waitcnt vmcnt(3)
	v_lshlrev_b32_e32 v39, 16, v192
	v_and_b32_e32 v53, 0xffff0000, v192
	v_and_b32_e32 v52, 0xffff0000, v190
	v_lshlrev_b32_e32 v54, 16, v191
	v_and_b32_e32 v36, 0xffff0000, v191
	v_mov_b32_e32 v34, v40
	v_mov_b32_e32 v35, v44
	v_mov_b32_e32 v44, v41
	v_pk_add_f32 v[34:35], v[34:35], v[38:39]
	v_pk_add_f32 v[38:39], v[44:45], v[52:53]
	v_mov_b32_e32 v40, v42
	v_mov_b32_e32 v41, v46
	v_mov_b32_e32 v46, v43
	v_pk_mul_f32 v[42:43], v[38:39], v[38:39]
	v_cvt_pk_bf16_f32 v44, v34, v38
	v_pk_fma_f32 v[42:43], v[34:35], v[34:35], v[42:43]
	v_add_f32_e32 v34, v48, v49
	v_lshlrev_b32_e32 v55, 16, v193
	v_add_f32_e32 v34, v34, v50
	v_and_b32_e32 v37, 0xffff0000, v193
	v_pk_add_f32 v[40:41], v[40:41], v[54:55]
	v_add_f32_e32 v34, v34, v51
	v_pk_add_f32 v[36:37], v[46:47], v[36:37]
	v_pk_fma_f32 v[42:43], v[40:41], v[40:41], v[42:43]
	v_add_f32_e32 v32, v34, v32
	v_pk_fma_f32 v[42:43], v[36:37], v[36:37], v[42:43]
	v_add_f32_e32 v32, v32, v33
	v_add_f32_e32 v32, v32, v42
	v_cvt_pk_bf16_f32 v45, v40, v36
	v_add_f32_e32 v71, v32, v43
	v_cvt_pk_bf16_f32 v32, v35, v39
	v_cvt_pk_bf16_f32 v33, v41, v37
	v_mov_b32_e32 v234, v44
	v_mov_b32_e32 v235, v45
	v_mov_b32_e32 v236, v32
	v_mov_b32_e32 v237, v33
	s_nop 1
	v_permlane32_swap_b32_e32 v234, v236
	v_permlane32_swap_b32_e32 v235, v237
	global_store_dwordx4 v[240:241], v[234:237], off offset:96

; __device__ __forceinline__ float bf_lo(unsigned u) { return __uint_as_float(u << 16); }
; __device__ __forceinline__ float bf_hi(unsigned u) { return __uint_as_float(u & 0xffff0000u); }
; template <int MODE>
; __device__ __forceinline__ void epi_resid(const f32x16 (&acc)[2][2], int nbase, int tbase, CP& p, const Grp& G) {
;     ...
;   for (int tb = 0; tb < 2; ++tb) {
;     const int tok = tbase + tb * 32 + l32;
;     const bool valid = tok < G.Mx;
;     float sq = 0.f;
;     if (valid) {
;       float* hp = p.H + (size_t)tok * 1024;
;       u16* hb = p.HB + (size_t)tok * 1024;
;       const float* rp = G.x + (size_t)tok * 1024;
; #pragma unroll
;       for (int nb = 0; nb < 2; ++nb)
; #pragma unroll
;         for (int i = 0; i < 4; ++i) {
;           const int n = nbase + nb * 32 + 8 * i + 4 * h;
;           f32x4 r;
;           if (MODE == 0) r = *(const f32x4*)(rp + n);
;           else { const u32x2 rb = *(const u32x2*)(hb + n); r = (f32x4){bf_lo(rb.x), bf_hi(rb.x), bf_lo(rb.y), bf_hi(rb.y)}; }
;           f32x4 v;
;           v.x = r.x + scale * acc[nb][tb][4 * i + 0];
;           v.y = r.y + scale * acc[nb][tb][4 * i + 1];
;           v.z = r.z + scale * acc[nb][tb][4 * i + 2];
;           v.w = r.w + scale * acc[nb][tb][4 * i + 3];
;           sq += v.x * v.x + v.y * v.y + v.z * v.z + v.w * v.w;
;           if (MODE == 2) *(f32x4*)(hp + n) = v;
;           else *(u32x2*)(hb + n) = (u32x2){pk_bf16(v.x, v.y), pk_bf16(v.z, v.w)};
;         }
;     }
;     sq += __shfl_xor(sq, 32);
;     if (valid && h == 0) atomicAdd(ssout + tok, sq);
;   }
.LBB0_130:
	s_or_b64 exec, exec, s[0:1]
	s_waitcnt lgkmcnt(0)
	v_or_b32_e32 v32, 32, v64
	v_cmp_gt_i32_e64 s[42:43], s62, v32
	v_mov_b32_e32 v34, 0
	s_and_saveexec_b64 s[34:35], s[42:43]
	s_cbranch_execz .LBB0_132
	v_ashrrev_i32_e32 v33, 31, v32
	v_lshlrev_b64 v[32:33], 11, v[32:33]
	v_lshl_add_u64 v[32:33], s[46:47], 0, v[32:33]
	v_lshl_add_u64 v[32:33], v[66:67], 1, v[32:33]
	global_load_dwordx2 v[178:179], v[32:33], off
	global_load_dwordx2 v[180:181], v[32:33], off offset:16
	global_load_dwordx2 v[182:183], v[32:33], off offset:32
	global_load_dwordx2 v[184:185], v[32:33], off offset:48
	global_load_dwordx2 v[186:187], v[32:33], off offset:64
	global_load_dwordx2 v[188:189], v[32:33], off offset:80
	global_load_dwordx2 v[190:191], v[32:33], off offset:96
	global_load_dwordx2 v[192:193], v[32:33], off offset:112
	s_nop 0
	v_mov_b32_e32 v40, v16
	v_mov_b32_e32 v41, v20
	v_mov_b32_e32 v20, v17
	v_mov_b32_e32 v42, v18
	v_mov_b32_e32 v43, v22
	v_mov_b32_e32 v22, v19
	s_waitcnt vmcnt(7)
	v_lshlrev_b32_e32 v38, 16, v178
	s_waitcnt vmcnt(6)
	v_lshlrev_b32_e32 v39, 16, v180
	v_pk_add_f32 v[38:39], v[40:41], v[38:39]
	v_and_b32_e32 v41, 0xffff0000, v180
	v_and_b32_e32 v40, 0xffff0000, v178
	v_pk_add_f32 v[20:21], v[20:21], v[40:41]
	v_lshlrev_b32_e32 v41, 16, v181
	v_lshlrev_b32_e32 v40, 16, v179
	v_and_b32_e32 v37, 0xffff0000, v181
	v_and_b32_e32 v36, 0xffff0000, v179
	v_pk_add_f32 v[40:41], v[42:43], v[40:41]
	v_pk_add_f32 v[18:19], v[22:23], v[36:37]
	v_cvt_pk_bf16_f32 v16, v38, v20
	v_cvt_pk_bf16_f32 v17, v40, v18
	v_mov_b32_e32 v222, v16
	v_mov_b32_e32 v223, v17
	v_pk_mul_f32 v[16:17], v[20:21], v[20:21]
	s_nop 0
	v_pk_fma_f32 v[16:17], v[38:39], v[38:39], v[16:17]
	s_nop 0
	v_pk_fma_f32 v[16:17], v[40:41], v[40:41], v[16:17]
	s_nop 0
	v_pk_fma_f32 v[16:17], v[18:19], v[18:19], v[16:17]
	v_cvt_pk_bf16_f32 v18, v39, v21
	v_cvt_pk_bf16_f32 v19, v41, v19
	v_mov_b32_e32 v224, v18
	v_mov_b32_e32 v225, v19
	v_lshrrev_b32_e32 v238, 2, v204
	v_and_b32_e32 v238, 8, v238
	v_mov_b32_e32 v239, 0
	v_lshl_add_u64 v[240:241], v[32:33], 0, v[238:239]
	v_permlane32_swap_b32_e32 v222, v224
	v_permlane32_swap_b32_e32 v223, v225
	global_store_dwordx4 v[240:241], v[222:225], off
	s_nop 0
	s_nop 0
	s_nop 0
	s_waitcnt vmcnt(6)
	v_lshlrev_b32_e32 v22, 16, v182
	s_waitcnt vmcnt(5)
	v_lshlrev_b32_e32 v23, 16, v184
	v_and_b32_e32 v35, 0xffff0000, v184
	v_and_b32_e32 v34, 0xffff0000, v182
	v_lshlrev_b32_e32 v36, 16, v183
	v_and_b32_e32 v20, 0xffff0000, v183
	v_mov_b32_e32 v18, v24
	v_mov_b32_e32 v19, v28
	v_mov_b32_e32 v28, v25
	v_lshlrev_b32_e32 v37, 16, v185
	v_pk_add_f32 v[22:23], v[18:19], v[22:23]
	v_pk_add_f32 v[24:25], v[28:29], v[34:35]
	v_mov_b32_e32 v18, v26
	v_mov_b32_e32 v19, v30
	v_pk_add_f32 v[28:29], v[18:19], v[36:37]
	v_pk_mul_f32 v[18:19], v[24:25], v[24:25]
	v_and_b32_e32 v21, 0xffff0000, v185
	v_mov_b32_e32 v30, v27
	v_pk_fma_f32 v[18:19], v[22:23], v[22:23], v[18:19]
	v_pk_add_f32 v[20:21], v[30:31], v[20:21]
	v_pk_fma_f32 v[18:19], v[28:29], v[28:29], v[18:19]
	v_cvt_pk_bf16_f32 v26, v22, v24
	v_pk_fma_f32 v[18:19], v[20:21], v[20:21], v[18:19]
	v_cvt_pk_bf16_f32 v27, v28, v20
	v_cvt_pk_bf16_f32 v20, v23, v25
	v_cvt_pk_bf16_f32 v21, v29, v21
	v_mov_b32_e32 v226, v26
	v_mov_b32_e32 v227, v27
	v_mov_b32_e32 v228, v20
	v_mov_b32_e32 v229, v21
	s_nop 1
	v_permlane32_swap_b32_e32 v226, v228
	v_permlane32_swap_b32_e32 v227, v229
	global_store_dwordx4 v[240:241], v[226:229], off offset:32
	s_nop 0
	s_nop 0
	s_nop 0
	s_waitcnt vmcnt(5)
	v_and_b32_e32 v26, 0xffff0000, v186
	s_waitcnt vmcnt(4)
	v_lshlrev_b32_e32 v25, 16, v188
	v_and_b32_e32 v27, 0xffff0000, v188
	v_lshlrev_b32_e32 v28, 16, v187
	v_and_b32_e32 v22, 0xffff0000, v187
	v_mov_b32_e32 v21, v4
	v_mov_b32_e32 v4, v1
	v_lshlrev_b32_e32 v24, 16, v186
	v_lshlrev_b32_e32 v29, 16, v189
	v_mov_b32_e32 v20, v0
	v_pk_add_f32 v[4:5], v[4:5], v[26:27]
	v_mov_b32_e32 v0, v2
	v_mov_b32_e32 v1, v6
	v_pk_add_f32 v[20:21], v[20:21], v[24:25]
	v_pk_add_f32 v[24:25], v[0:1], v[28:29]
	v_pk_mul_f32 v[0:1], v[4:5], v[4:5]
	v_and_b32_e32 v23, 0xffff0000, v189
	v_mov_b32_e32 v6, v3
	v_pk_fma_f32 v[0:1], v[20:21], v[20:21], v[0:1]
	v_pk_add_f32 v[2:3], v[6:7], v[22:23]
	v_pk_fma_f32 v[0:1], v[24:25], v[24:25], v[0:1]
	v_cvt_pk_bf16_f32 v6, v20, v4
	v_pk_fma_f32 v[0:1], v[2:3], v[2:3], v[0:1]
	v_cvt_pk_bf16_f32 v7, v24, v2
	v_cvt_pk_bf16_f32 v2, v21, v5
	v_cvt_pk_bf16_f32 v3, v25, v3
	v_mov_b32_e32 v230, v6
	v_mov_b32_e32 v231, v7
	v_mov_b32_e32 v232, v2
	v_mov_b32_e32 v233, v3
	s_nop 1
	v_permlane32_swap_b32_e32 v230, v232
	v_permlane32_swap_b32_e32 v231, v233
	global_store_dwordx4 v[240:241], v[230:233], off offset:64
	s_nop 0
	s_nop 0
	s_nop 0
	s_waitcnt vmcnt(4)
	v_lshlrev_b32_e32 v6, 16, v190
	s_waitcnt vmcnt(3)
	v_lshlrev_b32_e32 v7, 16, v192
	v_and_b32_e32 v21, 0xffff0000, v192
	v_and_b32_e32 v20, 0xffff0000, v190
	v_lshlrev_b32_e32 v22, 16, v191
	v_and_b32_e32 v4, 0xffff0000, v191
	v_mov_b32_e32 v2, v8
	v_mov_b32_e32 v3, v12
	v_mov_b32_e32 v12, v9
	v_pk_add_f32 v[2:3], v[2:3], v[6:7]
	v_pk_add_f32 v[6:7], v[12:13], v[20:21]
	v_mov_b32_e32 v8, v10
	v_mov_b32_e32 v9, v14
	v_mov_b32_e32 v14, v11
	v_pk_mul_f32 v[10:11], v[6:7], v[6:7]
	v_cvt_pk_bf16_f32 v12, v2, v6
	v_pk_fma_f32 v[10:11], v[2:3], v[2:3], v[10:11]
	v_add_f32_e32 v2, v16, v17
	v_lshlrev_b32_e32 v23, 16, v193
	v_add_f32_e32 v2, v2, v18
	v_and_b32_e32 v5, 0xffff0000, v193
	v_pk_add_f32 v[8:9], v[8:9], v[22:23]
	v_add_f32_e32 v2, v2, v19
	v_pk_add_f32 v[4:5], v[14:15], v[4:5]
	v_pk_fma_f32 v[10:11], v[8:9], v[8:9], v[10:11]
	v_add_f32_e32 v0, v2, v0
	v_pk_fma_f32 v[10:11], v[4:5], v[4:5], v[10:11]
	v_add_f32_e32 v0, v0, v1
	v_add_f32_e32 v0, v0, v10
	v_cvt_pk_bf16_f32 v13, v8, v4
	v_add_f32_e32 v34, v0, v11
	v_cvt_pk_bf16_f32 v0, v3, v7
	v_cvt_pk_bf16_f32 v1, v9, v5
	v_mov_b32_e32 v234, v12
	v_mov_b32_e32 v235, v13
	v_mov_b32_e32 v236, v0
	v_mov_b32_e32 v237, v1
	s_nop 1
	v_permlane32_swap_b32_e32 v234, v236
	v_permlane32_swap_b32_e32 v235, v237
	global_store_dwordx4 v[240:241], v[234:237], off offset:96

; __device__ __forceinline__ u16 bf16_1(float a) { return (u16)(pk_bf16(a, 0.f) & 0xffffu); }
; __device__ void run_phase(CP& p, int ph, char* lds) {
;     ...
;         for (int tb = 0; tb < 2; ++tb) {
;           const int tok = tbase + tb * 32 + l32;
;           if (tok < M) {
;             const float rs = rsqrtf(p.ss1[tok] * (1.f / 1024.f) + EPSN);
;             if (!G.meta && nbase >= 2048 && nbase < 3072) {
;               const int s = tok >> G.lgS, t = 16 + (tok & (G.S - 1));
;               const int Lp = (G.L + 63) & ~63;
;               const int pos = (t & ~12) | ((t & 4) << 1) | ((t & 8) >> 1);
;               u16* vt = p.VT + ((size_t)(s * 1024 + (nbase - 2048)) * Lp) + pos;
; #pragma unroll
;               for (int nb = 0; nb < 2; ++nb)
; #pragma unroll
;                 for (int r = 0; r < 16; ++r) {
;                   const int dvl = nb * 32 + 8 * (r >> 2) + 4 * h + (r & 3);
;                   vt[(size_t)dvl * Lp] = bf16_1(acc[nb][tb][r] * rs);
;                 }
;             } else {
;               u16* dst = Pout + (size_t)tok * NIN + nbase + 4 * h;
; #pragma unroll
;               for (int nb = 0; nb < 2; ++nb)
; #pragma unroll
;                 for (int i = 0; i < 4; ++i)
;                   *(u32x2*)(dst + nb * 32 + 8 * i) = (u32x2){pk_bf16(acc[nb][tb][4 * i] * rs, acc[nb][tb][4 * i + 1] * rs),
;                                                              pk_bf16(acc[nb][tb][4 * i + 2] * rs, acc[nb][tb][4 * i + 3] * rs)};
;             }
.LBB0_623:
	s_or_b64 exec, exec, s[6:7]
	v_mov_b32_e32 v147, v204
	v_lshl_add_u32 v154, v170, 8, v169
	v_lshl_or_b32 v144, v160, 7, v168
	v_and_or_b32 v146, v147, 31, v154
	v_and_b32_e32 v145, 0x1fffff8, v160
	v_lshrrev_b32_e32 v147, 3, v147
	v_cmp_eq_u32_e64 s[40:41], 16, v145
	v_ashrrev_i32_e32 v145, 31, v144
	v_and_b32_e32 v155, 4, v147
	v_add_u32_e32 v153, 0xfffff800, v144
	v_cmp_gt_i32_e64 s[42:43], s62, v146
	v_ashrrev_i32_e32 v147, 31, v146
	s_and_saveexec_b64 s[34:35], s[42:43]
	s_cbranch_execz .LBB0_628
	v_lshl_add_u64 v[150:151], v[146:147], 2, s[48:49]
	global_load_dword v148, v[150:151], off
	s_and_b64 s[0:1], s[86:87], s[40:41]
	s_xor_b64 s[0:1], s[0:1], -1
	s_waitcnt vmcnt(0)
	v_fmamk_f32 v148, v148, 0x3a800000, v205
	v_mul_f32_e32 v150, 0x4b800000, v148
	v_cmp_gt_f32_e64 s[42:43], s21, v148
	s_nop 1
	v_cndmask_b32_e64 v148, v148, v150, s[42:43]
	v_rsq_f32_e32 v148, v148
	s_nop 0
	v_mul_f32_e32 v150, 0x45800000, v148
	v_cndmask_b32_e64 v148, v148, v150, s[42:43]
	s_and_saveexec_b64 s[6:7], s[0:1]
	s_xor_b64 s[6:7], exec, s[6:7]
	s_cbranch_execz .LBB0_626
	v_mov_b64_e32 v[150:151], s[46:47]
	v_mad_i64_i32 v[150:151], s[0:1], v146, s74, v[150:151]
	v_lshl_add_u64 v[150:151], v[144:145], 1, v[150:151]
	v_lshlrev_b32_e32 v160, 1, v155
	v_lshl_add_u64 v[150:151], v[150:151], 0, v[160:161]
	v_lshl_add_u64 v[150:151], v[150:151], 0, v[160:161]
	v_pk_mul_f32 v[112:113], v[112:113], v[148:149] op_sel_hi:[1,0]
	v_pk_mul_f32 v[114:115], v[114:115], v[148:149] op_sel_hi:[1,0]
	v_pk_mul_f32 v[116:117], v[116:117], v[148:149] op_sel_hi:[1,0]
	v_pk_mul_f32 v[118:119], v[118:119], v[148:149] op_sel_hi:[1,0]
	v_cvt_pk_bf16_f32 v222, v112, v113
	v_cvt_pk_bf16_f32 v223, v114, v115
	v_cvt_pk_bf16_f32 v224, v116, v117
	v_cvt_pk_bf16_f32 v225, v118, v119
	s_nop 1
	v_permlane32_swap_b32_e32 v222, v224
	v_permlane32_swap_b32_e32 v223, v225
	global_store_dwordx4 v[150:151], v[222:225], off
	v_pk_mul_f32 v[120:121], v[120:121], v[148:149] op_sel_hi:[1,0]
	v_pk_mul_f32 v[122:123], v[122:123], v[148:149] op_sel_hi:[1,0]
	v_pk_mul_f32 v[124:125], v[124:125], v[148:149] op_sel_hi:[1,0]
	v_pk_mul_f32 v[126:127], v[126:127], v[148:149] op_sel_hi:[1,0]
	v_cvt_pk_bf16_f32 v226, v120, v121
	v_cvt_pk_bf16_f32 v227, v122, v123
	v_cvt_pk_bf16_f32 v228, v124, v125
	v_cvt_pk_bf16_f32 v229, v126, v127
	s_nop 1
	v_permlane32_swap_b32_e32 v226, v228
	v_permlane32_swap_b32_e32 v227, v229
	global_store_dwordx4 v[150:151], v[226:229], off offset:32
	v_pk_mul_f32 v[96:97], v[96:97], v[148:149] op_sel_hi:[1,0]
	v_pk_mul_f32 v[98:99], v[98:99], v[148:149] op_sel_hi:[1,0]
	v_pk_mul_f32 v[100:101], v[100:101], v[148:149] op_sel_hi:[1,0]
	v_pk_mul_f32 v[102:103], v[102:103], v[148:149] op_sel_hi:[1,0]
	v_cvt_pk_bf16_f32 v230, v96, v97
	v_cvt_pk_bf16_f32 v231, v98, v99
	v_cvt_pk_bf16_f32 v232, v100, v101
	v_cvt_pk_bf16_f32 v233, v102, v103
	s_nop 1
	v_permlane32_swap_b32_e32 v230, v232
	v_permlane32_swap_b32_e32 v231, v233
	global_store_dwordx4 v[150:151], v[230:233], off offset:64
	v_pk_mul_f32 v[104:105], v[104:105], v[148:149] op_sel_hi:[1,0]
	v_pk_mul_f32 v[106:107], v[106:107], v[148:149] op_sel_hi:[1,0]
	v_pk_mul_f32 v[108:109], v[108:109], v[148:149] op_sel_hi:[1,0]
	v_pk_mul_f32 v[110:111], v[110:111], v[148:149] op_sel_hi:[1,0]
	v_cvt_pk_bf16_f32 v234, v104, v105
	v_cvt_pk_bf16_f32 v235, v106, v107
	v_cvt_pk_bf16_f32 v236, v108, v109
	v_cvt_pk_bf16_f32 v237, v110, v111
	s_nop 1
	v_permlane32_swap_b32_e32 v234, v236
	v_permlane32_swap_b32_e32 v235, v237
	global_store_dwordx4 v[150:151], v[234:237], off offset:96

; __device__ __forceinline__ u16 bf16_1(float a) { return (u16)(pk_bf16(a, 0.f) & 0xffffu); }
; __device__ void run_phase(CP& p, int ph, char* lds) {
;     ...
;         for (int tb = 0; tb < 2; ++tb) {
;           const int tok = tbase + tb * 32 + l32;
;           if (tok < M) {
;             const float rs = rsqrtf(p.ss1[tok] * (1.f / 1024.f) + EPSN);
;             if (!G.meta && nbase >= 2048 && nbase < 3072) {
;               const int s = tok >> G.lgS, t = 16 + (tok & (G.S - 1));
;               const int Lp = (G.L + 63) & ~63;
;               const int pos = (t & ~12) | ((t & 4) << 1) | ((t & 8) >> 1);
;               u16* vt = p.VT + ((size_t)(s * 1024 + (nbase - 2048)) * Lp) + pos;
; #pragma unroll
;               for (int nb = 0; nb < 2; ++nb)
; #pragma unroll
;                 for (int r = 0; r < 16; ++r) {
;                   const int dvl = nb * 32 + 8 * (r >> 2) + 4 * h + (r & 3);
;                   vt[(size_t)dvl * Lp] = bf16_1(acc[nb][tb][r] * rs);
;                 }
;             } else {
;               u16* dst = Pout + (size_t)tok * NIN + nbase + 4 * h;
; #pragma unroll
;               for (int nb = 0; nb < 2; ++nb)
; #pragma unroll
;                 for (int i = 0; i < 4; ++i)
;                   *(u32x2*)(dst + nb * 32 + 8 * i) = (u32x2){pk_bf16(acc[nb][tb][4 * i] * rs, acc[nb][tb][4 * i + 1] * rs),
;                                                              pk_bf16(acc[nb][tb][4 * i + 2] * rs, acc[nb][tb][4 * i + 3] * rs)};
;             }
.LBB0_628:
	s_or_b64 exec, exec, s[34:35]
	v_or_b32_e32 v97, 32, v146
	v_cmp_gt_i32_e64 s[42:43], s62, v97
	s_and_saveexec_b64 s[34:35], s[42:43]
	s_cbranch_execz .LBB0_633
	v_lshl_add_u64 v[98:99], v[146:147], 2, s[48:49]
	global_load_dword v96, v[98:99], off offset:128
	s_and_b64 s[0:1], s[86:87], s[40:41]
	s_xor_b64 s[0:1], s[0:1], -1
	s_waitcnt vmcnt(0)
	v_fmamk_f32 v96, v96, 0x3a800000, v205
	v_mul_f32_e32 v98, 0x4b800000, v96
	v_cmp_gt_f32_e64 s[42:43], s21, v96
	s_nop 1
	v_cndmask_b32_e64 v96, v96, v98, s[42:43]
	v_rsq_f32_e32 v96, v96
	s_nop 0
	v_mul_f32_e32 v98, 0x45800000, v96
	v_cndmask_b32_e64 v96, v96, v98, s[42:43]
	s_and_saveexec_b64 s[6:7], s[0:1]
	s_xor_b64 s[6:7], exec, s[6:7]
	s_cbranch_execz .LBB0_631
	v_mov_b64_e32 v[98:99], s[46:47]
	v_mad_i64_i32 v[98:99], s[0:1], v97, s74, v[98:99]
	v_lshl_add_u64 v[98:99], v[144:145], 1, v[98:99]
	v_lshlrev_b32_e32 v160, 1, v155
	v_lshl_add_u64 v[98:99], v[98:99], 0, v[160:161]
	v_lshl_add_u64 v[98:99], v[98:99], 0, v[160:161]
	v_pk_mul_f32 v[80:81], v[80:81], v[96:97] op_sel_hi:[1,0]
	v_pk_mul_f32 v[82:83], v[82:83], v[96:97] op_sel_hi:[1,0]
	v_pk_mul_f32 v[84:85], v[84:85], v[96:97] op_sel_hi:[1,0]
	v_pk_mul_f32 v[86:87], v[86:87], v[96:97] op_sel_hi:[1,0]
	v_cvt_pk_bf16_f32 v222, v80, v81
	v_cvt_pk_bf16_f32 v223, v82, v83
	v_cvt_pk_bf16_f32 v224, v84, v85
	v_cvt_pk_bf16_f32 v225, v86, v87
	s_nop 1
	v_permlane32_swap_b32_e32 v222, v224
	v_permlane32_swap_b32_e32 v223, v225
	global_store_dwordx4 v[98:99], v[222:225], off
	v_pk_mul_f32 v[88:89], v[88:89], v[96:97] op_sel_hi:[1,0]
	v_pk_mul_f32 v[90:91], v[90:91], v[96:97] op_sel_hi:[1,0]
	v_pk_mul_f32 v[92:93], v[92:93], v[96:97] op_sel_hi:[1,0]
	v_pk_mul_f32 v[94:95], v[94:95], v[96:97] op_sel_hi:[1,0]
	v_cvt_pk_bf16_f32 v226, v88, v89
	v_cvt_pk_bf16_f32 v227, v90, v91
	v_cvt_pk_bf16_f32 v228, v92, v93
	v_cvt_pk_bf16_f32 v229, v94, v95
	s_nop 1
	v_permlane32_swap_b32_e32 v226, v228
	v_permlane32_swap_b32_e32 v227, v229
	global_store_dwordx4 v[98:99], v[226:229], off offset:32
	v_pk_mul_f32 v[64:65], v[64:65], v[96:97] op_sel_hi:[1,0]
	v_pk_mul_f32 v[66:67], v[66:67], v[96:97] op_sel_hi:[1,0]
	v_pk_mul_f32 v[68:69], v[68:69], v[96:97] op_sel_hi:[1,0]
	v_pk_mul_f32 v[70:71], v[70:71], v[96:97] op_sel_hi:[1,0]
	v_cvt_pk_bf16_f32 v230, v64, v65
	v_cvt_pk_bf16_f32 v231, v66, v67
	v_cvt_pk_bf16_f32 v232, v68, v69
	v_cvt_pk_bf16_f32 v233, v70, v71
	s_nop 1
	v_permlane32_swap_b32_e32 v230, v232
	v_permlane32_swap_b32_e32 v231, v233
	global_store_dwordx4 v[98:99], v[230:233], off offset:64
	v_pk_mul_f32 v[72:73], v[72:73], v[96:97] op_sel_hi:[1,0]
	v_pk_mul_f32 v[74:75], v[74:75], v[96:97] op_sel_hi:[1,0]
	v_pk_mul_f32 v[76:77], v[76:77], v[96:97] op_sel_hi:[1,0]
	v_pk_mul_f32 v[78:79], v[78:79], v[96:97] op_sel_hi:[1,0]
	v_cvt_pk_bf16_f32 v234, v72, v73
	v_cvt_pk_bf16_f32 v235, v74, v75
	v_cvt_pk_bf16_f32 v236, v76, v77
	v_cvt_pk_bf16_f32 v237, v78, v79
	s_nop 1
	v_permlane32_swap_b32_e32 v234, v236
	v_permlane32_swap_b32_e32 v235, v237
	global_store_dwordx4 v[98:99], v[234:237], off offset:96

; __device__ __forceinline__ u16 bf16_1(float a) { return (u16)(pk_bf16(a, 0.f) & 0xffffu); }
; __device__ void run_phase(CP& p, int ph, char* lds) {
;     ...
;         for (int tb = 0; tb < 2; ++tb) {
;           const int tok = tbase + tb * 32 + l32;
;           if (tok < M) {
;             const float rs = rsqrtf(p.ss1[tok] * (1.f / 1024.f) + EPSN);
;             if (!G.meta && nbase >= 2048 && nbase < 3072) {
;               const int s = tok >> G.lgS, t = 16 + (tok & (G.S - 1));
;               const int Lp = (G.L + 63) & ~63;
;               const int pos = (t & ~12) | ((t & 4) << 1) | ((t & 8) >> 1);
;               u16* vt = p.VT + ((size_t)(s * 1024 + (nbase - 2048)) * Lp) + pos;
; #pragma unroll
;               for (int nb = 0; nb < 2; ++nb)
; #pragma unroll
;                 for (int r = 0; r < 16; ++r) {
;                   const int dvl = nb * 32 + 8 * (r >> 2) + 4 * h + (r & 3);
;                   vt[(size_t)dvl * Lp] = bf16_1(acc[nb][tb][r] * rs);
;                 }
;             } else {
;               u16* dst = Pout + (size_t)tok * NIN + nbase + 4 * h;
; #pragma unroll
;               for (int nb = 0; nb < 2; ++nb)
; #pragma unroll
;                 for (int i = 0; i < 4; ++i)
;                   *(u32x2*)(dst + nb * 32 + 8 * i) = (u32x2){pk_bf16(acc[nb][tb][4 * i] * rs, acc[nb][tb][4 * i + 1] * rs),
;                                                              pk_bf16(acc[nb][tb][4 * i + 2] * rs, acc[nb][tb][4 * i + 3] * rs)};
;             }
.LBB0_633:
	s_or_b64 exec, exec, s[34:35]
	v_mov_b32_e32 v65, v204
	s_movk_i32 s0, 0x80
	v_and_b32_e32 v64, 31, v65
	v_add3_u32 v64, v154, v64, s0
	v_lshrrev_b32_e32 v65, 3, v65
	v_and_b32_e32 v67, 4, v65
	v_cmp_gt_i32_e64 s[42:43], s62, v64
	v_ashrrev_i32_e32 v65, 31, v64
	s_and_saveexec_b64 s[34:35], s[42:43]
	s_cbranch_execz .LBB0_638
	v_lshl_add_u64 v[68:69], v[64:65], 2, s[48:49]
	global_load_dword v66, v[68:69], off
	s_and_b64 s[0:1], s[86:87], s[40:41]
	s_xor_b64 s[0:1], s[0:1], -1
	s_waitcnt vmcnt(0)
	v_fmamk_f32 v66, v66, 0x3a800000, v205
	v_mul_f32_e32 v68, 0x4b800000, v66
	v_cmp_gt_f32_e64 s[42:43], s21, v66
	s_nop 1
	v_cndmask_b32_e64 v66, v66, v68, s[42:43]
	v_rsq_f32_e32 v66, v66
	s_nop 0
	v_mul_f32_e32 v68, 0x45800000, v66
	v_cndmask_b32_e64 v66, v66, v68, s[42:43]
	s_and_saveexec_b64 s[6:7], s[0:1]
	s_xor_b64 s[6:7], exec, s[6:7]
	s_cbranch_execz .LBB0_636
	v_mov_b64_e32 v[68:69], s[46:47]
	v_mad_i64_i32 v[68:69], s[0:1], v64, s74, v[68:69]
	v_lshl_add_u64 v[68:69], v[144:145], 1, v[68:69]
	v_lshlrev_b32_e32 v160, 1, v67
	v_lshl_add_u64 v[68:69], v[68:69], 0, v[160:161]
	v_lshl_add_u64 v[68:69], v[68:69], 0, v[160:161]
	v_pk_mul_f32 v[48:49], v[48:49], v[66:67] op_sel_hi:[1,0]
	v_pk_mul_f32 v[50:51], v[50:51], v[66:67] op_sel_hi:[1,0]
	v_pk_mul_f32 v[52:53], v[52:53], v[66:67] op_sel_hi:[1,0]
	v_pk_mul_f32 v[54:55], v[54:55], v[66:67] op_sel_hi:[1,0]
	v_cvt_pk_bf16_f32 v222, v48, v49
	v_cvt_pk_bf16_f32 v223, v50, v51
	v_cvt_pk_bf16_f32 v224, v52, v53
	v_cvt_pk_bf16_f32 v225, v54, v55
	s_nop 1
	v_permlane32_swap_b32_e32 v222, v224
	v_permlane32_swap_b32_e32 v223, v225
	global_store_dwordx4 v[68:69], v[222:225], off
	v_pk_mul_f32 v[56:57], v[56:57], v[66:67] op_sel_hi:[1,0]
	v_pk_mul_f32 v[58:59], v[58:59], v[66:67] op_sel_hi:[1,0]
	v_pk_mul_f32 v[60:61], v[60:61], v[66:67] op_sel_hi:[1,0]
	v_pk_mul_f32 v[62:63], v[62:63], v[66:67] op_sel_hi:[1,0]
	v_cvt_pk_bf16_f32 v226, v56, v57
	v_cvt_pk_bf16_f32 v227, v58, v59
	v_cvt_pk_bf16_f32 v228, v60, v61
	v_cvt_pk_bf16_f32 v229, v62, v63
	s_nop 1
	v_permlane32_swap_b32_e32 v226, v228
	v_permlane32_swap_b32_e32 v227, v229
	global_store_dwordx4 v[68:69], v[226:229], off offset:32
	v_pk_mul_f32 v[32:33], v[32:33], v[66:67] op_sel_hi:[1,0]
	v_pk_mul_f32 v[34:35], v[34:35], v[66:67] op_sel_hi:[1,0]
	v_pk_mul_f32 v[36:37], v[36:37], v[66:67] op_sel_hi:[1,0]
	v_pk_mul_f32 v[38:39], v[38:39], v[66:67] op_sel_hi:[1,0]
	v_cvt_pk_bf16_f32 v230, v32, v33
	v_cvt_pk_bf16_f32 v231, v34, v35
	v_cvt_pk_bf16_f32 v232, v36, v37
	v_cvt_pk_bf16_f32 v233, v38, v39
	s_nop 1
	v_permlane32_swap_b32_e32 v230, v232
	v_permlane32_swap_b32_e32 v231, v233
	global_store_dwordx4 v[68:69], v[230:233], off offset:64
	v_pk_mul_f32 v[40:41], v[40:41], v[66:67] op_sel_hi:[1,0]
	v_pk_mul_f32 v[42:43], v[42:43], v[66:67] op_sel_hi:[1,0]
	v_pk_mul_f32 v[44:45], v[44:45], v[66:67] op_sel_hi:[1,0]
	v_pk_mul_f32 v[46:47], v[46:47], v[66:67] op_sel_hi:[1,0]
	v_cvt_pk_bf16_f32 v234, v40, v41
	v_cvt_pk_bf16_f32 v235, v42, v43
	v_cvt_pk_bf16_f32 v236, v44, v45
	v_cvt_pk_bf16_f32 v237, v46, v47
	s_nop 1
	v_permlane32_swap_b32_e32 v234, v236
	v_permlane32_swap_b32_e32 v235, v237
	global_store_dwordx4 v[68:69], v[234:237], off offset:96

; __device__ __forceinline__ u16 bf16_1(float a) { return (u16)(pk_bf16(a, 0.f) & 0xffffu); }
; __device__ void run_phase(CP& p, int ph, char* lds) {
;     ...
;         for (int tb = 0; tb < 2; ++tb) {
;           const int tok = tbase + tb * 32 + l32;
;           if (tok < M) {
;             const float rs = rsqrtf(p.ss1[tok] * (1.f / 1024.f) + EPSN);
;             if (!G.meta && nbase >= 2048 && nbase < 3072) {
;               const int s = tok >> G.lgS, t = 16 + (tok & (G.S - 1));
;               const int Lp = (G.L + 63) & ~63;
;               const int pos = (t & ~12) | ((t & 4) << 1) | ((t & 8) >> 1);
;               u16* vt = p.VT + ((size_t)(s * 1024 + (nbase - 2048)) * Lp) + pos;
; #pragma unroll
;               for (int nb = 0; nb < 2; ++nb)
; #pragma unroll
;                 for (int r = 0; r < 16; ++r) {
;                   const int dvl = nb * 32 + 8 * (r >> 2) + 4 * h + (r & 3);
;                   vt[(size_t)dvl * Lp] = bf16_1(acc[nb][tb][r] * rs);
;                 }
;             } else {
;               u16* dst = Pout + (size_t)tok * NIN + nbase + 4 * h;
; #pragma unroll
;               for (int nb = 0; nb < 2; ++nb)
; #pragma unroll
;                 for (int i = 0; i < 4; ++i)
;                   *(u32x2*)(dst + nb * 32 + 8 * i) = (u32x2){pk_bf16(acc[nb][tb][4 * i] * rs, acc[nb][tb][4 * i + 1] * rs),
;                                                              pk_bf16(acc[nb][tb][4 * i + 2] * rs, acc[nb][tb][4 * i + 3] * rs)};
;             }
.LBB0_638:
	s_or_b64 exec, exec, s[34:35]
	v_or_b32_e32 v33, 32, v64
	v_cmp_gt_i32_e64 s[42:43], s62, v33
	s_and_saveexec_b64 s[34:35], s[42:43]
	s_cbranch_execz .LBB0_614
	v_lshl_add_u64 v[34:35], v[64:65], 2, s[48:49]
	global_load_dword v32, v[34:35], off offset:128
	s_and_b64 s[0:1], s[86:87], s[40:41]
	s_xor_b64 s[0:1], s[0:1], -1
	s_waitcnt vmcnt(0)
	v_fmamk_f32 v32, v32, 0x3a800000, v205
	v_cmp_gt_f32_e64 s[42:43], s21, v32
	v_mul_f32_e32 v34, 0x4b800000, v32
	s_nop 0
	v_cndmask_b32_e64 v32, v32, v34, s[42:43]
	v_rsq_f32_e32 v32, v32
	s_nop 0
	v_mul_f32_e32 v34, 0x45800000, v32
	v_cndmask_b32_e64 v32, v32, v34, s[42:43]
	s_and_saveexec_b64 s[6:7], s[0:1]
	s_xor_b64 s[6:7], exec, s[6:7]
	s_cbranch_execz .LBB0_641
	v_mov_b64_e32 v[34:35], s[46:47]
	v_mad_i64_i32 v[34:35], s[0:1], v33, s74, v[34:35]
	v_lshl_add_u64 v[34:35], v[144:145], 1, v[34:35]
	v_lshlrev_b32_e32 v160, 1, v67
	v_lshl_add_u64 v[34:35], v[34:35], 0, v[160:161]
	v_lshl_add_u64 v[34:35], v[34:35], 0, v[160:161]
	v_pk_mul_f32 v[16:17], v[16:17], v[32:33] op_sel_hi:[1,0]
	v_pk_mul_f32 v[18:19], v[18:19], v[32:33] op_sel_hi:[1,0]
	v_pk_mul_f32 v[20:21], v[20:21], v[32:33] op_sel_hi:[1,0]
	v_pk_mul_f32 v[22:23], v[22:23], v[32:33] op_sel_hi:[1,0]
	v_cvt_pk_bf16_f32 v222, v16, v17
	v_cvt_pk_bf16_f32 v223, v18, v19
	v_cvt_pk_bf16_f32 v224, v20, v21
	v_cvt_pk_bf16_f32 v225, v22, v23
	s_nop 1
	v_permlane32_swap_b32_e32 v222, v224
	v_permlane32_swap_b32_e32 v223, v225
	global_store_dwordx4 v[34:35], v[222:225], off
	v_pk_mul_f32 v[24:25], v[24:25], v[32:33] op_sel_hi:[1,0]
	v_pk_mul_f32 v[26:27], v[26:27], v[32:33] op_sel_hi:[1,0]
	v_pk_mul_f32 v[28:29], v[28:29], v[32:33] op_sel_hi:[1,0]
	v_pk_mul_f32 v[30:31], v[30:31], v[32:33] op_sel_hi:[1,0]
	v_cvt_pk_bf16_f32 v226, v24, v25
	v_cvt_pk_bf16_f32 v227, v26, v27
	v_cvt_pk_bf16_f32 v228, v28, v29
	v_cvt_pk_bf16_f32 v229, v30, v31
	s_nop 1
	v_permlane32_swap_b32_e32 v226, v228
	v_permlane32_swap_b32_e32 v227, v229
	global_store_dwordx4 v[34:35], v[226:229], off offset:32
	v_pk_mul_f32 v[0:1], v[0:1], v[32:33] op_sel_hi:[1,0]
	v_pk_mul_f32 v[2:3], v[2:3], v[32:33] op_sel_hi:[1,0]
	v_pk_mul_f32 v[4:5], v[4:5], v[32:33] op_sel_hi:[1,0]
	v_pk_mul_f32 v[6:7], v[6:7], v[32:33] op_sel_hi:[1,0]
	v_cvt_pk_bf16_f32 v230, v0, v1
	v_cvt_pk_bf16_f32 v231, v2, v3
	v_cvt_pk_bf16_f32 v232, v4, v5
	v_cvt_pk_bf16_f32 v233, v6, v7
	s_nop 1
	v_permlane32_swap_b32_e32 v230, v232
	v_permlane32_swap_b32_e32 v231, v233
	global_store_dwordx4 v[34:35], v[230:233], off offset:64
	v_pk_mul_f32 v[8:9], v[8:9], v[32:33] op_sel_hi:[1,0]
	v_pk_mul_f32 v[10:11], v[10:11], v[32:33] op_sel_hi:[1,0]
	v_pk_mul_f32 v[12:13], v[12:13], v[32:33] op_sel_hi:[1,0]
	v_pk_mul_f32 v[14:15], v[14:15], v[32:33] op_sel_hi:[1,0]
	v_cvt_pk_bf16_f32 v234, v8, v9
	v_cvt_pk_bf16_f32 v235, v10, v11
	v_cvt_pk_bf16_f32 v236, v12, v13
	v_cvt_pk_bf16_f32 v237, v14, v15
	s_nop 1
	v_permlane32_swap_b32_e32 v234, v236
	v_permlane32_swap_b32_e32 v235, v237
	global_store_dwordx4 v[34:35], v[234:237], off offset:96

; __device__ __forceinline__ float bf_lo(unsigned u) { return __uint_as_float(u << 16); }
; __device__ __forceinline__ float bf_hi(unsigned u) { return __uint_as_float(u & 0xffff0000u); }
; template <int MODE>
; __device__ __forceinline__ void epi_resid(const f32x16 (&acc)[2][2], int nbase, int tbase, CP& p, const Grp& G) {
;     ...
;   for (int tb = 0; tb < 2; ++tb) {
;     const int tok = tbase + tb * 32 + l32;
;     const bool valid = tok < G.Mx;
;     float sq = 0.f;
;     if (valid) {
;       float* hp = p.H + (size_t)tok * 1024;
;       u16* hb = p.HB + (size_t)tok * 1024;
;       const float* rp = G.x + (size_t)tok * 1024;
; #pragma unroll
;       for (int nb = 0; nb < 2; ++nb)
; #pragma unroll
;         for (int i = 0; i < 4; ++i) {
;           const int n = nbase + nb * 32 + 8 * i + 4 * h;
;           f32x4 r;
;           if (MODE == 0) r = *(const f32x4*)(rp + n);
;           else { const u32x2 rb = *(const u32x2*)(hb + n); r = (f32x4){bf_lo(rb.x), bf_hi(rb.x), bf_lo(rb.y), bf_hi(rb.y)}; }
;           f32x4 v;
;           v.x = r.x + scale * acc[nb][tb][4 * i + 0];
;           v.y = r.y + scale * acc[nb][tb][4 * i + 1];
;           v.z = r.z + scale * acc[nb][tb][4 * i + 2];
;           v.w = r.w + scale * acc[nb][tb][4 * i + 3];
;           sq += v.x * v.x + v.y * v.y + v.z * v.z + v.w * v.w;
;           if (MODE == 2) *(f32x4*)(hp + n) = v;
;           else *(u32x2*)(hb + n) = (u32x2){pk_bf16(v.x, v.y), pk_bf16(v.z, v.w)};
;         }
;     }
;     sq += __shfl_xor(sq, 32);
;     if (valid && h == 0) atomicAdd(ssout + tok, sq);
;   }
.LBB0_663:
	s_or_b64 exec, exec, s[6:7]
	v_mov_b32_e32 v144, v204
	v_lshl_or_b32 v154, v169, 7, v166
	v_lshl_add_u32 v155, v168, 8, v167
	v_mov_b32_e32 v150, 0
	v_bfe_u32 v168, v144, 5, 1
	v_and_or_b32 v144, v144, 31, v155
	v_lshl_or_b32 v146, v168, 2, v154
	v_cmp_gt_i32_e64 s[42:43], s62, v144
	v_ashrrev_i32_e32 v145, 31, v144
	v_ashrrev_i32_e32 v147, 31, v146
	s_and_saveexec_b64 s[34:35], s[42:43]
	s_cbranch_execz .LBB0_665
	v_lshlrev_b64 v[150:151], 12, v[144:145]
	v_lshl_add_u64 v[150:151], s[28:29], 0, v[150:151]
	v_lshl_add_u64 v[150:151], v[146:147], 2, v[150:151]
	global_load_dwordx4 v[174:177], v[150:151], off
	global_load_dwordx4 v[178:181], v[150:151], off offset:32
	global_load_dwordx4 v[182:185], v[150:151], off offset:64
	global_load_dwordx4 v[186:189], v[150:151], off offset:96
	v_lshlrev_b64 v[148:149], 11, v[144:145]
	v_lshl_add_u64 v[148:149], s[46:47], 0, v[148:149]
	v_lshl_add_u64 v[148:149], v[146:147], 1, v[148:149]
	s_waitcnt vmcnt(3)
	v_pk_fma_f32 v[170:171], v[112:113], 0.5, v[174:175] op_sel_hi:[1,0,1]
	v_pk_fma_f32 v[172:173], v[114:115], 0.5, v[176:177] op_sel_hi:[1,0,1]
	v_cvt_pk_bf16_f32 v112, v170, v171
	v_cvt_pk_bf16_f32 v113, v172, v173
	v_mov_b32_e32 v222, v112
	v_mov_b32_e32 v223, v113
	s_nop 0
	s_waitcnt vmcnt(2)
	v_pk_fma_f32 v[116:117], v[116:117], 0.5, v[178:179] op_sel_hi:[1,0,1]
	v_pk_fma_f32 v[114:115], v[118:119], 0.5, v[180:181] op_sel_hi:[1,0,1]
	v_mov_b32_e32 v118, v171
	v_mov_b32_e32 v119, v117
	v_mov_b32_e32 v112, v170
	v_mov_b32_e32 v113, v116
	v_pk_mul_f32 v[118:119], v[118:119], v[118:119]
	v_cvt_pk_bf16_f32 v116, v116, v117
	v_cvt_pk_bf16_f32 v117, v114, v115
	v_pk_fma_f32 v[112:113], v[112:113], v[112:113], v[118:119]
	v_mov_b32_e32 v118, v172
	v_mov_b32_e32 v119, v114
	v_mov_b32_e32 v224, v116
	v_mov_b32_e32 v225, v117
	v_lshrrev_b32_e32 v238, 2, v204
	v_and_b32_e32 v238, 8, v238
	v_mov_b32_e32 v239, 0
	v_lshl_add_u64 v[240:241], v[148:149], 0, v[238:239]
	v_permlane32_swap_b32_e32 v222, v224
	v_permlane32_swap_b32_e32 v223, v225
	global_store_dwordx4 v[240:241], v[222:225], off
	v_pk_fma_f32 v[112:113], v[118:119], v[118:119], v[112:113]
	v_mov_b32_e32 v119, v115
	s_nop 0
	v_mov_b32_e32 v118, v173
	v_pk_fma_f32 v[112:113], v[118:119], v[118:119], v[112:113]
	s_waitcnt vmcnt(2)
	v_pk_fma_f32 v[118:119], v[120:121], 0.5, v[182:183] op_sel_hi:[1,0,1]
	v_pk_fma_f32 v[120:121], v[122:123], 0.5, v[184:185] op_sel_hi:[1,0,1]
	v_cvt_pk_bf16_f32 v114, v118, v119
	v_cvt_pk_bf16_f32 v115, v120, v121
	v_mov_b32_e32 v226, v114
	v_mov_b32_e32 v227, v115
	s_nop 0
	s_waitcnt vmcnt(1)
	v_pk_fma_f32 v[122:123], v[124:125], 0.5, v[186:187] op_sel_hi:[1,0,1]
	v_mov_b32_e32 v114, v118
	v_mov_b32_e32 v118, v119
	v_mov_b32_e32 v119, v123
	v_pk_fma_f32 v[116:117], v[126:127], 0.5, v[188:189] op_sel_hi:[1,0,1]
	v_mov_b32_e32 v115, v122
	v_pk_mul_f32 v[118:119], v[118:119], v[118:119]
	s_nop 0
	v_pk_fma_f32 v[114:115], v[114:115], v[114:115], v[118:119]
	v_mov_b32_e32 v118, v120
	v_mov_b32_e32 v119, v116
	v_pk_fma_f32 v[114:115], v[118:119], v[118:119], v[114:115]
	v_mov_b32_e32 v118, v121
	v_mov_b32_e32 v119, v117
	v_pk_fma_f32 v[114:115], v[118:119], v[118:119], v[114:115]
	v_cvt_pk_bf16_f32 v118, v122, v123
	v_cvt_pk_bf16_f32 v119, v116, v117
	v_mov_b32_e32 v228, v118
	v_mov_b32_e32 v229, v119
	s_nop 1
	v_permlane32_swap_b32_e32 v226, v228
	v_permlane32_swap_b32_e32 v227, v229
	global_store_dwordx4 v[240:241], v[226:229], off offset:32
	global_load_dwordx4 v[174:177], v[150:151], off offset:128
	global_load_dwordx4 v[178:181], v[150:151], off offset:160
	global_load_dwordx4 v[182:185], v[150:151], off offset:192
	global_load_dwordx4 v[186:189], v[150:151], off offset:224
	s_waitcnt vmcnt(3)
	v_pk_fma_f32 v[116:117], v[96:97], 0.5, v[174:175] op_sel_hi:[1,0,1]
	v_pk_fma_f32 v[118:119], v[98:99], 0.5, v[176:177] op_sel_hi:[1,0,1]
	v_cvt_pk_bf16_f32 v96, v116, v117
	v_cvt_pk_bf16_f32 v97, v118, v119
	v_mov_b32_e32 v230, v96
	v_mov_b32_e32 v231, v97
	s_nop 0
	s_waitcnt vmcnt(2)
	v_pk_fma_f32 v[96:97], v[100:101], 0.5, v[178:179] op_sel_hi:[1,0,1]
	v_pk_fma_f32 v[98:99], v[102:103], 0.5, v[180:181] op_sel_hi:[1,0,1]
	v_mov_b32_e32 v102, v117
	v_mov_b32_e32 v103, v97
	v_mov_b32_e32 v100, v116
	v_mov_b32_e32 v101, v96
	v_pk_mul_f32 v[102:103], v[102:103], v[102:103]
	v_cvt_pk_bf16_f32 v96, v96, v97
	v_cvt_pk_bf16_f32 v97, v98, v99
	v_pk_fma_f32 v[100:101], v[100:101], v[100:101], v[102:103]
	v_mov_b32_e32 v102, v118
	v_mov_b32_e32 v103, v98
	v_mov_b32_e32 v232, v96
	v_mov_b32_e32 v233, v97
	s_nop 1
	v_permlane32_swap_b32_e32 v230, v232
	v_permlane32_swap_b32_e32 v231, v233
	global_store_dwordx4 v[240:241], v[230:233], off offset:64
	v_pk_fma_f32 v[100:101], v[102:103], v[102:103], v[100:101]
	v_mov_b32_e32 v103, v99
	s_nop 0
	v_mov_b32_e32 v102, v119
	v_pk_fma_f32 v[100:101], v[102:103], v[102:103], v[100:101]
	s_waitcnt vmcnt(2)
	v_pk_fma_f32 v[102:103], v[104:105], 0.5, v[182:183] op_sel_hi:[1,0,1]
	v_pk_fma_f32 v[104:105], v[106:107], 0.5, v[184:185] op_sel_hi:[1,0,1]
	v_cvt_pk_bf16_f32 v96, v102, v103
	v_cvt_pk_bf16_f32 v97, v104, v105
	v_mov_b32_e32 v234, v96
	v_mov_b32_e32 v235, v97
	s_nop 0
	v_mov_b32_e32 v106, v102
	v_mov_b32_e32 v102, v103
	s_waitcnt vmcnt(1)
	v_pk_fma_f32 v[96:97], v[108:109], 0.5, v[186:187] op_sel_hi:[1,0,1]
	s_nop 0
	v_mov_b32_e32 v103, v97
	v_pk_fma_f32 v[98:99], v[110:111], 0.5, v[188:189] op_sel_hi:[1,0,1]
	v_mov_b32_e32 v107, v96
	v_pk_mul_f32 v[102:103], v[102:103], v[102:103]
	v_cvt_pk_bf16_f32 v96, v96, v97
	v_pk_fma_f32 v[102:103], v[106:107], v[106:107], v[102:103]
	v_mov_b32_e32 v106, v104
	v_mov_b32_e32 v107, v98
	v_pk_fma_f32 v[102:103], v[106:107], v[106:107], v[102:103]
	v_mov_b32_e32 v104, v105
	v_mov_b32_e32 v105, v99
	v_pk_fma_f32 v[102:103], v[104:105], v[104:105], v[102:103]
	v_add_f32_e32 v104, v112, v113
	v_add_f32_e32 v104, v104, v114
	v_add_f32_e32 v104, v104, v115
	v_add_f32_e32 v100, v104, v100
	v_add_f32_e32 v100, v100, v101
	v_add_f32_e32 v100, v100, v102
	v_add_f32_e32 v150, v100, v103
	v_cvt_pk_bf16_f32 v97, v98, v99
	v_mov_b32_e32 v236, v96
	v_mov_b32_e32 v237, v97
	s_nop 1
	v_permlane32_swap_b32_e32 v234, v236
	v_permlane32_swap_b32_e32 v235, v237
	global_store_dwordx4 v[240:241], v[234:237], off offset:96

; __device__ __forceinline__ float bf_lo(unsigned u) { return __uint_as_float(u << 16); }
; __device__ __forceinline__ float bf_hi(unsigned u) { return __uint_as_float(u & 0xffff0000u); }
; template <int MODE>
; __device__ __forceinline__ void epi_resid(const f32x16 (&acc)[2][2], int nbase, int tbase, CP& p, const Grp& G) {
;     ...
;   for (int tb = 0; tb < 2; ++tb) {
;     const int tok = tbase + tb * 32 + l32;
;     const bool valid = tok < G.Mx;
;     float sq = 0.f;
;     if (valid) {
;       float* hp = p.H + (size_t)tok * 1024;
;       u16* hb = p.HB + (size_t)tok * 1024;
;       const float* rp = G.x + (size_t)tok * 1024;
; #pragma unroll
;       for (int nb = 0; nb < 2; ++nb)
; #pragma unroll
;         for (int i = 0; i < 4; ++i) {
;           const int n = nbase + nb * 32 + 8 * i + 4 * h;
;           f32x4 r;
;           if (MODE == 0) r = *(const f32x4*)(rp + n);
;           else { const u32x2 rb = *(const u32x2*)(hb + n); r = (f32x4){bf_lo(rb.x), bf_hi(rb.x), bf_lo(rb.y), bf_hi(rb.y)}; }
;           f32x4 v;
;           v.x = r.x + scale * acc[nb][tb][4 * i + 0];
;           v.y = r.y + scale * acc[nb][tb][4 * i + 1];
;           v.z = r.z + scale * acc[nb][tb][4 * i + 2];
;           v.w = r.w + scale * acc[nb][tb][4 * i + 3];
;           sq += v.x * v.x + v.y * v.y + v.z * v.z + v.w * v.w;
;           if (MODE == 2) *(f32x4*)(hp + n) = v;
;           else *(u32x2*)(hb + n) = (u32x2){pk_bf16(v.x, v.y), pk_bf16(v.z, v.w)};
;         }
;     }
;     sq += __shfl_xor(sq, 32);
;     if (valid && h == 0) atomicAdd(ssout + tok, sq);
;   }
.LBB0_667:
	s_or_b64 exec, exec, s[0:1]
	s_waitcnt lgkmcnt(0)
	v_or_b32_e32 v96, 32, v144
	v_cmp_gt_i32_e64 s[42:43], s62, v96
	v_mov_b32_e32 v98, 0
	s_and_saveexec_b64 s[34:35], s[42:43]
	s_cbranch_execz .LBB0_669
	v_ashrrev_i32_e32 v97, 31, v96
	v_lshlrev_b64 v[98:99], 11, v[96:97]
	v_lshlrev_b64 v[96:97], 12, v[96:97]
	v_lshl_add_u64 v[96:97], s[28:29], 0, v[96:97]
	v_lshl_add_u64 v[106:107], s[46:47], 0, v[98:99]
	v_lshl_add_u64 v[98:99], v[146:147], 2, v[96:97]
	global_load_dwordx4 v[174:177], v[98:99], off
	global_load_dwordx4 v[178:181], v[98:99], off offset:32
	global_load_dwordx4 v[182:185], v[98:99], off offset:64
	global_load_dwordx4 v[186:189], v[98:99], off offset:96
	v_lshl_add_u64 v[96:97], v[146:147], 1, v[106:107]
	s_waitcnt vmcnt(3)
	v_pk_fma_f32 v[102:103], v[80:81], 0.5, v[174:175] op_sel_hi:[1,0,1]
	v_pk_fma_f32 v[104:105], v[82:83], 0.5, v[176:177] op_sel_hi:[1,0,1]
	v_cvt_pk_bf16_f32 v80, v102, v103
	v_cvt_pk_bf16_f32 v81, v104, v105
	v_mov_b32_e32 v222, v80
	v_mov_b32_e32 v223, v81
	s_nop 0
	s_waitcnt vmcnt(2)
	v_pk_fma_f32 v[84:85], v[84:85], 0.5, v[178:179] op_sel_hi:[1,0,1]
	v_pk_fma_f32 v[82:83], v[86:87], 0.5, v[180:181] op_sel_hi:[1,0,1]
	v_mov_b32_e32 v86, v103
	v_mov_b32_e32 v87, v85
	v_mov_b32_e32 v80, v102
	v_mov_b32_e32 v81, v84
	v_pk_mul_f32 v[86:87], v[86:87], v[86:87]
	v_cvt_pk_bf16_f32 v84, v84, v85
	v_cvt_pk_bf16_f32 v85, v82, v83
	v_pk_fma_f32 v[80:81], v[80:81], v[80:81], v[86:87]
	v_mov_b32_e32 v86, v104
	v_mov_b32_e32 v87, v82
	v_mov_b32_e32 v224, v84
	v_mov_b32_e32 v225, v85
	v_lshrrev_b32_e32 v238, 2, v204
	v_and_b32_e32 v238, 8, v238
	v_mov_b32_e32 v239, 0
	v_lshl_add_u64 v[240:241], v[96:97], 0, v[238:239]
	v_permlane32_swap_b32_e32 v222, v224
	v_permlane32_swap_b32_e32 v223, v225
	global_store_dwordx4 v[240:241], v[222:225], off
	v_pk_fma_f32 v[80:81], v[86:87], v[86:87], v[80:81]
	v_mov_b32_e32 v87, v83
	s_nop 0
	v_mov_b32_e32 v86, v105
	v_pk_fma_f32 v[80:81], v[86:87], v[86:87], v[80:81]
	s_waitcnt vmcnt(2)
	v_pk_fma_f32 v[86:87], v[88:89], 0.5, v[182:183] op_sel_hi:[1,0,1]
	v_pk_fma_f32 v[88:89], v[90:91], 0.5, v[184:185] op_sel_hi:[1,0,1]
	v_cvt_pk_bf16_f32 v82, v86, v87
	v_cvt_pk_bf16_f32 v83, v88, v89
	v_mov_b32_e32 v226, v82
	v_mov_b32_e32 v227, v83
	s_nop 0
	s_waitcnt vmcnt(1)
	v_pk_fma_f32 v[90:91], v[92:93], 0.5, v[186:187] op_sel_hi:[1,0,1]
	v_mov_b32_e32 v82, v86
	v_mov_b32_e32 v86, v87
	v_mov_b32_e32 v87, v91
	v_pk_fma_f32 v[84:85], v[94:95], 0.5, v[188:189] op_sel_hi:[1,0,1]
	v_mov_b32_e32 v83, v90
	v_pk_mul_f32 v[86:87], v[86:87], v[86:87]
	s_nop 0
	v_pk_fma_f32 v[82:83], v[82:83], v[82:83], v[86:87]
	v_mov_b32_e32 v86, v88
	v_mov_b32_e32 v87, v84
	v_pk_fma_f32 v[82:83], v[86:87], v[86:87], v[82:83]
	v_mov_b32_e32 v86, v89
	v_mov_b32_e32 v87, v85
	v_pk_fma_f32 v[82:83], v[86:87], v[86:87], v[82:83]
	v_cvt_pk_bf16_f32 v86, v90, v91
	v_cvt_pk_bf16_f32 v87, v84, v85
	v_mov_b32_e32 v228, v86
	v_mov_b32_e32 v229, v87
	s_nop 1
	v_permlane32_swap_b32_e32 v226, v228
	v_permlane32_swap_b32_e32 v227, v229
	global_store_dwordx4 v[240:241], v[226:229], off offset:32
	global_load_dwordx4 v[174:177], v[98:99], off offset:128
	global_load_dwordx4 v[178:181], v[98:99], off offset:160
	global_load_dwordx4 v[182:185], v[98:99], off offset:192
	global_load_dwordx4 v[186:189], v[98:99], off offset:224
	s_waitcnt vmcnt(3)
	v_pk_fma_f32 v[84:85], v[64:65], 0.5, v[174:175] op_sel_hi:[1,0,1]
	v_pk_fma_f32 v[86:87], v[66:67], 0.5, v[176:177] op_sel_hi:[1,0,1]
	v_cvt_pk_bf16_f32 v64, v84, v85
	v_cvt_pk_bf16_f32 v65, v86, v87
	v_mov_b32_e32 v230, v64
	v_mov_b32_e32 v231, v65
	s_nop 0
	s_waitcnt vmcnt(2)
	v_pk_fma_f32 v[64:65], v[68:69], 0.5, v[178:179] op_sel_hi:[1,0,1]
	v_pk_fma_f32 v[66:67], v[70:71], 0.5, v[180:181] op_sel_hi:[1,0,1]
	v_mov_b32_e32 v70, v85
	v_mov_b32_e32 v71, v65
	v_mov_b32_e32 v68, v84
	v_mov_b32_e32 v69, v64
	v_pk_mul_f32 v[70:71], v[70:71], v[70:71]
	v_cvt_pk_bf16_f32 v64, v64, v65
	v_cvt_pk_bf16_f32 v65, v66, v67
	v_pk_fma_f32 v[68:69], v[68:69], v[68:69], v[70:71]
	v_mov_b32_e32 v70, v86
	v_mov_b32_e32 v71, v66
	v_mov_b32_e32 v232, v64
	v_mov_b32_e32 v233, v65
	s_nop 1
	v_permlane32_swap_b32_e32 v230, v232
	v_permlane32_swap_b32_e32 v231, v233
	global_store_dwordx4 v[240:241], v[230:233], off offset:64
	v_pk_fma_f32 v[68:69], v[70:71], v[70:71], v[68:69]
	v_mov_b32_e32 v71, v67
	s_nop 0
	v_mov_b32_e32 v70, v87
	v_pk_fma_f32 v[68:69], v[70:71], v[70:71], v[68:69]
	s_waitcnt vmcnt(2)
	v_pk_fma_f32 v[70:71], v[72:73], 0.5, v[182:183] op_sel_hi:[1,0,1]
	v_pk_fma_f32 v[72:73], v[74:75], 0.5, v[184:185] op_sel_hi:[1,0,1]
	v_cvt_pk_bf16_f32 v64, v70, v71
	v_cvt_pk_bf16_f32 v65, v72, v73
	v_mov_b32_e32 v234, v64
	v_mov_b32_e32 v235, v65
	s_nop 0
	v_mov_b32_e32 v74, v70
	v_mov_b32_e32 v70, v71
	s_waitcnt vmcnt(1)
	v_pk_fma_f32 v[64:65], v[76:77], 0.5, v[186:187] op_sel_hi:[1,0,1]
	s_nop 0
	v_mov_b32_e32 v71, v65
	v_pk_fma_f32 v[66:67], v[78:79], 0.5, v[188:189] op_sel_hi:[1,0,1]
	v_mov_b32_e32 v75, v64
	v_pk_mul_f32 v[70:71], v[70:71], v[70:71]
	v_cvt_pk_bf16_f32 v64, v64, v65
	v_pk_fma_f32 v[70:71], v[74:75], v[74:75], v[70:71]
	v_mov_b32_e32 v74, v72
	v_mov_b32_e32 v75, v66
	v_pk_fma_f32 v[70:71], v[74:75], v[74:75], v[70:71]
	v_mov_b32_e32 v72, v73
	v_mov_b32_e32 v73, v67
	v_pk_fma_f32 v[70:71], v[72:73], v[72:73], v[70:71]
	v_add_f32_e32 v72, v80, v81
	v_add_f32_e32 v72, v72, v82
	v_add_f32_e32 v72, v72, v83
	v_add_f32_e32 v68, v72, v68
	v_add_f32_e32 v68, v68, v69
	v_add_f32_e32 v68, v68, v70
	v_add_f32_e32 v98, v68, v71
	v_cvt_pk_bf16_f32 v65, v66, v67
	v_mov_b32_e32 v236, v64
	v_mov_b32_e32 v237, v65
	s_nop 1
	v_permlane32_swap_b32_e32 v234, v236
	v_permlane32_swap_b32_e32 v235, v237
	global_store_dwordx4 v[240:241], v[234:237], off offset:96

; __device__ __forceinline__ float bf_lo(unsigned u) { return __uint_as_float(u << 16); }
; __device__ __forceinline__ float bf_hi(unsigned u) { return __uint_as_float(u & 0xffff0000u); }
; template <int MODE>
; __device__ __forceinline__ void epi_resid(const f32x16 (&acc)[2][2], int nbase, int tbase, CP& p, const Grp& G) {
;     ...
;   for (int tb = 0; tb < 2; ++tb) {
;     const int tok = tbase + tb * 32 + l32;
;     const bool valid = tok < G.Mx;
;     float sq = 0.f;
;     if (valid) {
;       float* hp = p.H + (size_t)tok * 1024;
;       u16* hb = p.HB + (size_t)tok * 1024;
;       const float* rp = G.x + (size_t)tok * 1024;
; #pragma unroll
;       for (int nb = 0; nb < 2; ++nb)
; #pragma unroll
;         for (int i = 0; i < 4; ++i) {
;           const int n = nbase + nb * 32 + 8 * i + 4 * h;
;           f32x4 r;
;           if (MODE == 0) r = *(const f32x4*)(rp + n);
;           else { const u32x2 rb = *(const u32x2*)(hb + n); r = (f32x4){bf_lo(rb.x), bf_hi(rb.x), bf_lo(rb.y), bf_hi(rb.y)}; }
;           f32x4 v;
;           v.x = r.x + scale * acc[nb][tb][4 * i + 0];
;           v.y = r.y + scale * acc[nb][tb][4 * i + 1];
;           v.z = r.z + scale * acc[nb][tb][4 * i + 2];
;           v.w = r.w + scale * acc[nb][tb][4 * i + 3];
;           sq += v.x * v.x + v.y * v.y + v.z * v.z + v.w * v.w;
;           if (MODE == 2) *(f32x4*)(hp + n) = v;
;           else *(u32x2*)(hb + n) = (u32x2){pk_bf16(v.x, v.y), pk_bf16(v.z, v.w)};
;         }
;     }
;     sq += __shfl_xor(sq, 32);
;     if (valid && h == 0) atomicAdd(ssout + tok, sq);
;   }
.LBB0_671:
	s_or_b64 exec, exec, s[0:1]
	s_waitcnt lgkmcnt(0)
	v_mov_b32_e32 v64, v204
	s_movk_i32 s0, 0x80
	v_and_b32_e32 v65, 31, v64
	v_bfe_u32 v72, v64, 5, 1
	v_add3_u32 v64, v155, v65, s0
	v_lshl_or_b32 v66, v72, 2, v154
	v_cmp_gt_i32_e64 s[42:43], s62, v64
	v_mov_b32_e32 v70, 0
	v_ashrrev_i32_e32 v65, 31, v64
	v_ashrrev_i32_e32 v67, 31, v66
	s_and_saveexec_b64 s[34:35], s[42:43]
	s_cbranch_execz .LBB0_673
	v_lshlrev_b64 v[70:71], 12, v[64:65]
	v_lshl_add_u64 v[70:71], s[28:29], 0, v[70:71]
	v_lshl_add_u64 v[70:71], v[66:67], 2, v[70:71]
	global_load_dwordx4 v[174:177], v[70:71], off
	global_load_dwordx4 v[178:181], v[70:71], off offset:32
	global_load_dwordx4 v[182:185], v[70:71], off offset:64
	global_load_dwordx4 v[186:189], v[70:71], off offset:96
	v_lshlrev_b64 v[68:69], 11, v[64:65]
	v_lshl_add_u64 v[68:69], s[46:47], 0, v[68:69]
	v_lshl_add_u64 v[68:69], v[66:67], 1, v[68:69]
	s_waitcnt vmcnt(3)
	v_pk_fma_f32 v[74:75], v[48:49], 0.5, v[174:175] op_sel_hi:[1,0,1]
	v_pk_fma_f32 v[76:77], v[50:51], 0.5, v[176:177] op_sel_hi:[1,0,1]
	v_cvt_pk_bf16_f32 v48, v74, v75
	v_cvt_pk_bf16_f32 v49, v76, v77
	v_mov_b32_e32 v222, v48
	v_mov_b32_e32 v223, v49
	s_nop 0
	s_waitcnt vmcnt(2)
	v_pk_fma_f32 v[52:53], v[52:53], 0.5, v[178:179] op_sel_hi:[1,0,1]
	v_pk_fma_f32 v[50:51], v[54:55], 0.5, v[180:181] op_sel_hi:[1,0,1]
	v_mov_b32_e32 v54, v75
	v_mov_b32_e32 v55, v53
	v_mov_b32_e32 v48, v74
	v_mov_b32_e32 v49, v52
	v_pk_mul_f32 v[54:55], v[54:55], v[54:55]
	v_cvt_pk_bf16_f32 v52, v52, v53
	v_cvt_pk_bf16_f32 v53, v50, v51
	v_pk_fma_f32 v[48:49], v[48:49], v[48:49], v[54:55]
	v_mov_b32_e32 v54, v76
	v_mov_b32_e32 v55, v50
	v_mov_b32_e32 v224, v52
	v_mov_b32_e32 v225, v53
	v_lshrrev_b32_e32 v238, 2, v204
	v_and_b32_e32 v238, 8, v238
	v_mov_b32_e32 v239, 0
	v_lshl_add_u64 v[240:241], v[68:69], 0, v[238:239]
	v_permlane32_swap_b32_e32 v222, v224
	v_permlane32_swap_b32_e32 v223, v225
	global_store_dwordx4 v[240:241], v[222:225], off
	v_pk_fma_f32 v[48:49], v[54:55], v[54:55], v[48:49]
	v_mov_b32_e32 v55, v51
	s_nop 0
	v_mov_b32_e32 v54, v77
	v_pk_fma_f32 v[48:49], v[54:55], v[54:55], v[48:49]
	s_waitcnt vmcnt(2)
	v_pk_fma_f32 v[54:55], v[56:57], 0.5, v[182:183] op_sel_hi:[1,0,1]
	v_pk_fma_f32 v[56:57], v[58:59], 0.5, v[184:185] op_sel_hi:[1,0,1]
	v_cvt_pk_bf16_f32 v50, v54, v55
	v_cvt_pk_bf16_f32 v51, v56, v57
	v_mov_b32_e32 v226, v50
	v_mov_b32_e32 v227, v51
	s_nop 0
	s_waitcnt vmcnt(1)
	v_pk_fma_f32 v[58:59], v[60:61], 0.5, v[186:187] op_sel_hi:[1,0,1]
	v_mov_b32_e32 v50, v54
	v_mov_b32_e32 v54, v55
	v_mov_b32_e32 v55, v59
	v_pk_fma_f32 v[52:53], v[62:63], 0.5, v[188:189] op_sel_hi:[1,0,1]
	v_mov_b32_e32 v51, v58
	v_pk_mul_f32 v[54:55], v[54:55], v[54:55]
	s_nop 0
	v_pk_fma_f32 v[50:51], v[50:51], v[50:51], v[54:55]
	v_mov_b32_e32 v54, v56
	v_mov_b32_e32 v55, v52
	v_pk_fma_f32 v[50:51], v[54:55], v[54:55], v[50:51]
	v_mov_b32_e32 v54, v57
	v_mov_b32_e32 v55, v53
	v_pk_fma_f32 v[50:51], v[54:55], v[54:55], v[50:51]
	v_cvt_pk_bf16_f32 v54, v58, v59
	v_cvt_pk_bf16_f32 v55, v52, v53
	v_mov_b32_e32 v228, v54
	v_mov_b32_e32 v229, v55
	s_nop 1
	v_permlane32_swap_b32_e32 v226, v228
	v_permlane32_swap_b32_e32 v227, v229
	global_store_dwordx4 v[240:241], v[226:229], off offset:32
	global_load_dwordx4 v[174:177], v[70:71], off offset:128
	global_load_dwordx4 v[178:181], v[70:71], off offset:160
	global_load_dwordx4 v[182:185], v[70:71], off offset:192
	global_load_dwordx4 v[186:189], v[70:71], off offset:224
	s_waitcnt vmcnt(3)
	v_pk_fma_f32 v[52:53], v[32:33], 0.5, v[174:175] op_sel_hi:[1,0,1]
	v_pk_fma_f32 v[54:55], v[34:35], 0.5, v[176:177] op_sel_hi:[1,0,1]
	v_cvt_pk_bf16_f32 v32, v52, v53
	v_cvt_pk_bf16_f32 v33, v54, v55
	v_mov_b32_e32 v230, v32
	v_mov_b32_e32 v231, v33
	s_nop 0
	s_waitcnt vmcnt(2)
	v_pk_fma_f32 v[32:33], v[36:37], 0.5, v[178:179] op_sel_hi:[1,0,1]
	v_pk_fma_f32 v[34:35], v[38:39], 0.5, v[180:181] op_sel_hi:[1,0,1]
	v_mov_b32_e32 v38, v53
	v_mov_b32_e32 v39, v33
	v_mov_b32_e32 v36, v52
	v_mov_b32_e32 v37, v32
	v_pk_mul_f32 v[38:39], v[38:39], v[38:39]
	v_cvt_pk_bf16_f32 v32, v32, v33
	v_cvt_pk_bf16_f32 v33, v34, v35
	v_pk_fma_f32 v[36:37], v[36:37], v[36:37], v[38:39]
	v_mov_b32_e32 v38, v54
	v_mov_b32_e32 v39, v34
	v_mov_b32_e32 v232, v32
	v_mov_b32_e32 v233, v33
	s_nop 1
	v_permlane32_swap_b32_e32 v230, v232
	v_permlane32_swap_b32_e32 v231, v233
	global_store_dwordx4 v[240:241], v[230:233], off offset:64
	v_pk_fma_f32 v[36:37], v[38:39], v[38:39], v[36:37]
	v_mov_b32_e32 v39, v35
	s_nop 0
	v_mov_b32_e32 v38, v55
	v_pk_fma_f32 v[36:37], v[38:39], v[38:39], v[36:37]
	s_waitcnt vmcnt(2)
	v_pk_fma_f32 v[38:39], v[40:41], 0.5, v[182:183] op_sel_hi:[1,0,1]
	v_pk_fma_f32 v[40:41], v[42:43], 0.5, v[184:185] op_sel_hi:[1,0,1]
	v_cvt_pk_bf16_f32 v32, v38, v39
	v_cvt_pk_bf16_f32 v33, v40, v41
	v_mov_b32_e32 v234, v32
	v_mov_b32_e32 v235, v33
	s_nop 0
	v_mov_b32_e32 v42, v38
	v_mov_b32_e32 v38, v39
	s_waitcnt vmcnt(1)
	v_pk_fma_f32 v[32:33], v[44:45], 0.5, v[186:187] op_sel_hi:[1,0,1]
	s_nop 0
	v_mov_b32_e32 v39, v33
	v_pk_fma_f32 v[34:35], v[46:47], 0.5, v[188:189] op_sel_hi:[1,0,1]
	v_mov_b32_e32 v43, v32
	v_pk_mul_f32 v[38:39], v[38:39], v[38:39]
	v_cvt_pk_bf16_f32 v32, v32, v33
	v_pk_fma_f32 v[38:39], v[42:43], v[42:43], v[38:39]
	v_mov_b32_e32 v42, v40
	v_mov_b32_e32 v43, v34
	v_pk_fma_f32 v[38:39], v[42:43], v[42:43], v[38:39]
	v_mov_b32_e32 v40, v41
	v_mov_b32_e32 v41, v35
	v_pk_fma_f32 v[38:39], v[40:41], v[40:41], v[38:39]
	v_add_f32_e32 v40, v48, v49
	v_add_f32_e32 v40, v40, v50
	v_add_f32_e32 v40, v40, v51
	v_add_f32_e32 v36, v40, v36
	v_add_f32_e32 v36, v36, v37
	v_add_f32_e32 v36, v36, v38
	v_add_f32_e32 v70, v36, v39
	v_cvt_pk_bf16_f32 v33, v34, v35
	v_mov_b32_e32 v236, v32
	v_mov_b32_e32 v237, v33
	s_nop 1
	v_permlane32_swap_b32_e32 v234, v236
	v_permlane32_swap_b32_e32 v235, v237
	global_store_dwordx4 v[240:241], v[234:237], off offset:96

; __device__ __forceinline__ float bf_lo(unsigned u) { return __uint_as_float(u << 16); }
; __device__ __forceinline__ float bf_hi(unsigned u) { return __uint_as_float(u & 0xffff0000u); }
; template <int MODE>
; __device__ __forceinline__ void epi_resid(const f32x16 (&acc)[2][2], int nbase, int tbase, CP& p, const Grp& G) {
;     ...
;   for (int tb = 0; tb < 2; ++tb) {
;     const int tok = tbase + tb * 32 + l32;
;     const bool valid = tok < G.Mx;
;     float sq = 0.f;
;     if (valid) {
;       float* hp = p.H + (size_t)tok * 1024;
;       u16* hb = p.HB + (size_t)tok * 1024;
;       const float* rp = G.x + (size_t)tok * 1024;
; #pragma unroll
;       for (int nb = 0; nb < 2; ++nb)
; #pragma unroll
;         for (int i = 0; i < 4; ++i) {
;           const int n = nbase + nb * 32 + 8 * i + 4 * h;
;           f32x4 r;
;           if (MODE == 0) r = *(const f32x4*)(rp + n);
;           else { const u32x2 rb = *(const u32x2*)(hb + n); r = (f32x4){bf_lo(rb.x), bf_hi(rb.x), bf_lo(rb.y), bf_hi(rb.y)}; }
;           f32x4 v;
;           v.x = r.x + scale * acc[nb][tb][4 * i + 0];
;           v.y = r.y + scale * acc[nb][tb][4 * i + 1];
;           v.z = r.z + scale * acc[nb][tb][4 * i + 2];
;           v.w = r.w + scale * acc[nb][tb][4 * i + 3];
;           sq += v.x * v.x + v.y * v.y + v.z * v.z + v.w * v.w;
;           if (MODE == 2) *(f32x4*)(hp + n) = v;
;           else *(u32x2*)(hb + n) = (u32x2){pk_bf16(v.x, v.y), pk_bf16(v.z, v.w)};
;         }
;     }
;     sq += __shfl_xor(sq, 32);
;     if (valid && h == 0) atomicAdd(ssout + tok, sq);
;   }
.LBB0_675:
	s_or_b64 exec, exec, s[0:1]
	s_waitcnt lgkmcnt(0)
	v_or_b32_e32 v32, 32, v64
	v_cmp_gt_i32_e64 s[42:43], s62, v32
	v_mov_b32_e32 v34, 0
	s_and_saveexec_b64 s[34:35], s[42:43]
	s_cbranch_execz .LBB0_677
	v_ashrrev_i32_e32 v33, 31, v32
	v_lshlrev_b64 v[34:35], 11, v[32:33]
	v_lshlrev_b64 v[32:33], 12, v[32:33]
	v_lshl_add_u64 v[32:33], s[28:29], 0, v[32:33]
	v_lshl_add_u64 v[40:41], s[46:47], 0, v[34:35]
	v_lshl_add_u64 v[34:35], v[66:67], 2, v[32:33]
	global_load_dwordx4 v[174:177], v[34:35], off
	global_load_dwordx4 v[178:181], v[34:35], off offset:32
	global_load_dwordx4 v[182:185], v[34:35], off offset:64
	global_load_dwordx4 v[186:189], v[34:35], off offset:96
	v_lshl_add_u64 v[32:33], v[66:67], 1, v[40:41]
	s_waitcnt vmcnt(3)
	v_pk_fma_f32 v[36:37], v[16:17], 0.5, v[174:175] op_sel_hi:[1,0,1]
	v_pk_fma_f32 v[38:39], v[18:19], 0.5, v[176:177] op_sel_hi:[1,0,1]
	v_cvt_pk_bf16_f32 v16, v36, v37
	v_cvt_pk_bf16_f32 v17, v38, v39
	v_mov_b32_e32 v222, v16
	v_mov_b32_e32 v223, v17
	s_nop 0
	s_waitcnt vmcnt(2)
	v_pk_fma_f32 v[20:21], v[20:21], 0.5, v[178:179] op_sel_hi:[1,0,1]
	v_pk_fma_f32 v[18:19], v[22:23], 0.5, v[180:181] op_sel_hi:[1,0,1]
	v_mov_b32_e32 v22, v37
	v_mov_b32_e32 v23, v21
	v_mov_b32_e32 v16, v36
	v_mov_b32_e32 v17, v20
	v_pk_mul_f32 v[22:23], v[22:23], v[22:23]
	v_cvt_pk_bf16_f32 v20, v20, v21
	v_cvt_pk_bf16_f32 v21, v18, v19
	v_pk_fma_f32 v[16:17], v[16:17], v[16:17], v[22:23]
	v_mov_b32_e32 v22, v38
	v_mov_b32_e32 v23, v18
	v_mov_b32_e32 v224, v20
	v_mov_b32_e32 v225, v21
	v_lshrrev_b32_e32 v238, 2, v204
	v_and_b32_e32 v238, 8, v238
	v_mov_b32_e32 v239, 0
	v_lshl_add_u64 v[240:241], v[32:33], 0, v[238:239]
	v_permlane32_swap_b32_e32 v222, v224
	v_permlane32_swap_b32_e32 v223, v225
	global_store_dwordx4 v[240:241], v[222:225], off
	v_pk_fma_f32 v[16:17], v[22:23], v[22:23], v[16:17]
	v_mov_b32_e32 v23, v19
	s_nop 0
	v_mov_b32_e32 v22, v39
	v_pk_fma_f32 v[16:17], v[22:23], v[22:23], v[16:17]
	s_waitcnt vmcnt(2)
	v_pk_fma_f32 v[22:23], v[24:25], 0.5, v[182:183] op_sel_hi:[1,0,1]
	v_pk_fma_f32 v[24:25], v[26:27], 0.5, v[184:185] op_sel_hi:[1,0,1]
	v_cvt_pk_bf16_f32 v18, v22, v23
	v_cvt_pk_bf16_f32 v19, v24, v25
	v_mov_b32_e32 v226, v18
	v_mov_b32_e32 v227, v19
	s_nop 0
	s_waitcnt vmcnt(1)
	v_pk_fma_f32 v[26:27], v[28:29], 0.5, v[186:187] op_sel_hi:[1,0,1]
	v_mov_b32_e32 v18, v22
	v_mov_b32_e32 v22, v23
	v_mov_b32_e32 v23, v27
	v_pk_fma_f32 v[20:21], v[30:31], 0.5, v[188:189] op_sel_hi:[1,0,1]
	v_mov_b32_e32 v19, v26
	v_pk_mul_f32 v[22:23], v[22:23], v[22:23]
	s_nop 0
	v_pk_fma_f32 v[18:19], v[18:19], v[18:19], v[22:23]
	v_mov_b32_e32 v22, v24
	v_mov_b32_e32 v23, v20
	v_pk_fma_f32 v[18:19], v[22:23], v[22:23], v[18:19]
	v_mov_b32_e32 v22, v25
	v_mov_b32_e32 v23, v21
	v_pk_fma_f32 v[18:19], v[22:23], v[22:23], v[18:19]
	v_cvt_pk_bf16_f32 v22, v26, v27
	v_cvt_pk_bf16_f32 v23, v20, v21
	v_mov_b32_e32 v228, v22
	v_mov_b32_e32 v229, v23
	s_nop 1
	v_permlane32_swap_b32_e32 v226, v228
	v_permlane32_swap_b32_e32 v227, v229
	global_store_dwordx4 v[240:241], v[226:229], off offset:32
	global_load_dwordx4 v[174:177], v[34:35], off offset:128
	global_load_dwordx4 v[178:181], v[34:35], off offset:160
	global_load_dwordx4 v[182:185], v[34:35], off offset:192
	global_load_dwordx4 v[186:189], v[34:35], off offset:224
	s_waitcnt vmcnt(3)
	v_pk_fma_f32 v[20:21], v[0:1], 0.5, v[174:175] op_sel_hi:[1,0,1]
	v_pk_fma_f32 v[22:23], v[2:3], 0.5, v[176:177] op_sel_hi:[1,0,1]
	v_cvt_pk_bf16_f32 v0, v20, v21
	v_cvt_pk_bf16_f32 v1, v22, v23
	v_mov_b32_e32 v230, v0
	v_mov_b32_e32 v231, v1
	s_nop 0
	s_waitcnt vmcnt(2)
	v_pk_fma_f32 v[0:1], v[4:5], 0.5, v[178:179] op_sel_hi:[1,0,1]
	v_pk_fma_f32 v[2:3], v[6:7], 0.5, v[180:181] op_sel_hi:[1,0,1]
	v_mov_b32_e32 v6, v21
	v_mov_b32_e32 v7, v1
	v_mov_b32_e32 v4, v20
	v_mov_b32_e32 v5, v0
	v_pk_mul_f32 v[6:7], v[6:7], v[6:7]
	v_cvt_pk_bf16_f32 v0, v0, v1
	v_cvt_pk_bf16_f32 v1, v2, v3
	v_pk_fma_f32 v[4:5], v[4:5], v[4:5], v[6:7]
	v_mov_b32_e32 v6, v22
	v_mov_b32_e32 v7, v2
	v_mov_b32_e32 v232, v0
	v_mov_b32_e32 v233, v1
	s_nop 1
	v_permlane32_swap_b32_e32 v230, v232
	v_permlane32_swap_b32_e32 v231, v233
	global_store_dwordx4 v[240:241], v[230:233], off offset:64
	v_pk_fma_f32 v[4:5], v[6:7], v[6:7], v[4:5]
	v_mov_b32_e32 v7, v3
	s_nop 0
	v_mov_b32_e32 v6, v23
	v_pk_fma_f32 v[4:5], v[6:7], v[6:7], v[4:5]
	s_waitcnt vmcnt(2)
	v_pk_fma_f32 v[6:7], v[8:9], 0.5, v[182:183] op_sel_hi:[1,0,1]
	v_pk_fma_f32 v[8:9], v[10:11], 0.5, v[184:185] op_sel_hi:[1,0,1]
	v_cvt_pk_bf16_f32 v0, v6, v7
	v_cvt_pk_bf16_f32 v1, v8, v9
	v_mov_b32_e32 v234, v0
	v_mov_b32_e32 v235, v1
	s_nop 0
	v_mov_b32_e32 v10, v6
	v_mov_b32_e32 v6, v7
	s_waitcnt vmcnt(1)
	v_pk_fma_f32 v[0:1], v[12:13], 0.5, v[186:187] op_sel_hi:[1,0,1]
	s_nop 0
	v_mov_b32_e32 v7, v1
	v_pk_fma_f32 v[2:3], v[14:15], 0.5, v[188:189] op_sel_hi:[1,0,1]
	v_mov_b32_e32 v11, v0
	v_pk_mul_f32 v[6:7], v[6:7], v[6:7]
	v_cvt_pk_bf16_f32 v0, v0, v1
	v_pk_fma_f32 v[6:7], v[10:11], v[10:11], v[6:7]
	v_mov_b32_e32 v10, v8
	v_mov_b32_e32 v11, v2
	v_pk_fma_f32 v[6:7], v[10:11], v[10:11], v[6:7]
	v_mov_b32_e32 v8, v9
	v_mov_b32_e32 v9, v3
	v_pk_fma_f32 v[6:7], v[8:9], v[8:9], v[6:7]
	v_add_f32_e32 v8, v16, v17
	v_add_f32_e32 v8, v8, v18
	v_add_f32_e32 v8, v8, v19
	v_add_f32_e32 v4, v8, v4
	v_add_f32_e32 v4, v4, v5
	v_add_f32_e32 v4, v4, v6
	v_add_f32_e32 v34, v4, v7
	v_cvt_pk_bf16_f32 v1, v2, v3
	v_mov_b32_e32 v236, v0
	v_mov_b32_e32 v237, v1
	s_nop 1
	v_permlane32_swap_b32_e32 v234, v236
	v_permlane32_swap_b32_e32 v235, v237
	global_store_dwordx4 v[240:241], v[234:237], off offset:96
